# attention: 32-column key window per wave (column bases 0,8,24,32), two key tiles per row in local chunks
# speedup vs baseline: 1.0103x; 1.0103x over previous
; __device__ __forceinline__ void attn_phase(const Params& P, char* smem_raw) {
;     ...
;   int dco[4][4];
; #pragma unroll
;   for (int reg = 0; reg < 4; ++reg) {
;     const int c = wid * 16 + (lane >> 4) * 4 + reg;
;     const int cs = min(max(c - 8, 0), 48);
; #pragma unroll
;     for (int q4 = 0; q4 < 4; ++q4) {
;       const int kc = q4 * 16 + (lane & 15);
;       dco[reg][q4] = (kc >= cs && kc < cs + 16) ? (kc - c + 15) : 465;
;     }
;   }
;   int t = VBID;
;   __syncthreads();
;   if (t < 8192) {
;     const int h0 = t & 15;
;     for (int idx = tid; idx < 930; idx += VTHR) sm_rpb[idx] = (idx < 465) ? P.rpb[h0 * 465 + idx] * 1.4426950408889634f : -1e30f;
;     ATT_ISSUE(t, 0)
;     ATT_QLOAD(t)
;   }
.LBB0_1489:
	s_cmp_gt_i32 s34, 12
	s_cselect_b64 s[0:1], -1, 0
	s_cmp_lt_i32 s35, 13
	s_cselect_b64 s[4:5], -1, 0
	s_or_b64 s[0:1], s[0:1], s[4:5]
	s_and_b64 vcc, exec, s[0:1]
	s_cbranch_vccnz .LBB0_1555
	s_waitcnt vmcnt(5)
	v_lshl_add_u32 v109, s2, 1, v153
	s_movk_i32 s0, 0x2000
	v_mov_b32_e32 v0, v153
	v_cmp_gt_i32_e32 vcc, s0, v109
	s_barrier
	s_and_saveexec_b64 s[42:43], vcc
	s_cbranch_execz .LBB0_1501
	v_readlane_b32 s0, v252, 0
	v_readlane_b32 s1, v252, 1
	v_readfirstlane_b32 s3, v153
	s_nop 3
	s_sub_u32 s0, s0, 0x170
	s_subb_u32 s1, s1, 0
	s_load_dwordx2 s[12:13], s[0:1], 0xb8
	s_load_dwordx2 s[8:9], s[0:1], 0x130
	s_load_dwordx4 s[4:7], s[0:1], 0x148
	s_load_dwordx2 s[10:11], s[0:1], 0x158
	s_lshl_b32 s100, s2, 1
	s_add_u32 s3, s100, s3
	s_and_b32 s101, s3, 15
	s_lshl_b32 s3, s3, 8
	s_waitcnt lgkmcnt(0)
	s_lshl_b32 s100, s101, 7
	s_add_u32 s4, s4, s100
	s_addc_u32 s5, s5, 0
	s_add_u32 s10, s10, s100
	s_addc_u32 s11, s11, 0
	s_lshl_b32 s100, s101, 20
	s_add_u32 s6, s6, s100
	s_addc_u32 s7, s7, 0
	s_lshl_b32 s100, s101, 15
	s_add_u32 s8, s8, s100
	s_addc_u32 s9, s9, 0
	s_mul_i32 s100, s101, 0x744
	s_add_u32 s12, s12, s100
	s_addc_u32 s13, s13, 0
	v_and_b32_e32 v112, 0xff, v152
	v_and_b32_e32 v113, 63, v152
	v_bfe_u32 v114, v152, 6, 2
	v_lshrrev_b32_e32 v115, 4, v113
	v_and_b32_e32 v116, 15, v113
	v_mul_u32_u24_e32 v117, 0x12000, v153
	v_add_u32_e32 v117, 16, v117
	v_and_b32_e32 v118, 7, v116
	v_lshrrev_b32_e32 v119, 1, v114
	v_add_u32_e32 v119, v119, v114
	v_lshlrev_b32_e32 v119, 3, v119
	v_xor_b32_e32 v121, v115, v118
	v_lshl_add_u32 v122, v116, 7, v117
	v_lshl_add_u32 v149, v121, 4, v122
	v_xor_b32_e32 v121, 4, v121
	v_lshl_add_u32 v224, v121, 4, v122
	v_lshl_add_u32 v144, v119, 7, v149
	v_lshl_add_u32 v145, v119, 7, v224
	v_lshl_add_u32 v124, v116, 8, v117
	v_add_u32_e32 v124, 0x4000, v124
	v_lshrrev_b32_e32 v123, 2, v119
	v_add_u32_e32 v125, 0, v115
	v_xor_b32_e32 v125, v125, v116
	v_lshl_add_u32 v225, v125, 4, v124
	v_add_u32_e32 v125, 4, v115
	v_xor_b32_e32 v125, v125, v116
	v_lshl_add_u32 v226, v125, 4, v124
	v_add_u32_e32 v125, 8, v115
	v_xor_b32_e32 v125, v125, v116
	v_lshl_add_u32 v227, v125, 4, v124
	v_add_u32_e32 v125, 12, v115
	v_xor_b32_e32 v125, v125, v116
	v_lshl_add_u32 v228, v125, 4, v124
	v_add3_u32 v125, v123, 0, v115
	v_xor_b32_e32 v125, v125, v116
	v_lshl_add_u32 v146, v125, 4, v124
	v_add3_u32 v125, v123, 4, v115
	v_xor_b32_e32 v125, v125, v116
	v_lshl_add_u32 v147, v125, 4, v124
	v_lshrrev_b32_e32 v126, 3, v112
	v_and_b32_e32 v127, 7, v112
	v_and_b32_e32 v128, 7, v126
	v_xor_b32_e32 v128, v127, v128
	v_lshl_add_u32 v125, v126, 7, v117
	v_lshl_add_u32 v150, v128, 4, v125
	v_lshrrev_b32_e32 v129, 4, v112
	v_and_b32_e32 v130, 15, v112
	v_and_b32_e32 v125, 7, v130
	v_lshlrev_b32_e32 v125, 1, v125
	v_xor_b32_e32 v125, v125, v129
	v_lshl_add_u32 v128, v129, 8, v117
	v_lshl_add_u32 v151, v125, 4, v128
	v_xor_b32_e32 v125, 1, v125
	v_lshl_add_u32 v229, v125, 4, v128
	v_lshrrev_b32_e32 v125, 3, v130
	v_lshl_add_u32 v151, v125, 3, v151
	v_lshl_add_u32 v229, v125, 3, v229
	v_add_u32_e32 v151, 0x4000, v151
	v_add_u32_e32 v229, 0x4000, v229
	v_mul_u32_u24_e32 v125, 0x1800, v126
	v_lshl_add_u32 v154, v127, 4, v125
	v_add_u32_e32 v155, 0x30000, v154
	v_add_u32_e32 v156, 0x60000, v154
	v_add_u32_e32 v157, 0x90000, v154
	v_lshlrev_b32_e32 v125, 14, v129
	v_lshl_add_u32 v158, v130, 4, v125
	v_add_u32_e32 v159, 0x40000, v158
	v_add_u32_e32 v160, 0x80000, v158
	v_add_u32_e32 v161, 0xc0000, v158
	v_lshlrev_b32_e32 v125, 9, v129
	v_lshl_add_u32 v162, v130, 4, v125
	v_add_u32_e32 v163, 0x2000, v162
	v_add_u32_e32 v164, 0x4000, v162
	v_add_u32_e32 v165, 0x6000, v162
	v_lshl_add_u32 v131, v114, 4, v116
	v_mul_u32_u24_e32 v125, 0x1800, v131
	v_lshl_add_u32 v166, v115, 4, v125
	v_lshlrev_b32_e32 v125, 11, v131
	v_lshl_add_u32 v167, v115, 3, v125
	v_sub_u32_e64 v132, v131, 8 clamp
	v_min_u32_e32 v132, 48, v132
	v_mov_b32_e32 v210, 0x7c
	v_lshl_add_u32 v133, v115, 2, v119
	v_add_u32_e32 v134, 0, v133
	v_sub_u32_e32 v135, v134, v132
	v_cmp_gt_u32_e32 vcc, 16, v135
	v_sub_u32_e32 v136, v134, v131
	v_lshlrev_b32_e32 v136, 2, v136
	v_add_u32_e32 v136, 60, v136
	v_cndmask_b32_e32 v168, v210, v136, vcc
	v_add_u32_e32 v134, 1, v133
	v_sub_u32_e32 v135, v134, v132
	v_cmp_gt_u32_e32 vcc, 16, v135
	v_sub_u32_e32 v136, v134, v131
	v_lshlrev_b32_e32 v136, 2, v136
	v_add_u32_e32 v136, 60, v136
	v_cndmask_b32_e32 v169, v210, v136, vcc
	v_add_u32_e32 v134, 2, v133
	v_sub_u32_e32 v135, v134, v132
	v_cmp_gt_u32_e32 vcc, 16, v135
	v_sub_u32_e32 v136, v134, v131
	v_lshlrev_b32_e32 v136, 2, v136
	v_add_u32_e32 v136, 60, v136
	v_cndmask_b32_e32 v170, v210, v136, vcc
	v_add_u32_e32 v134, 3, v133
	v_sub_u32_e32 v135, v134, v132
	v_cmp_gt_u32_e32 vcc, 16, v135
	v_sub_u32_e32 v136, v134, v131
	v_lshlrev_b32_e32 v136, 2, v136
	v_add_u32_e32 v136, 60, v136
	v_cndmask_b32_e32 v171, v210, v136, vcc
	v_add_u32_e32 v134, 16, v133
	v_sub_u32_e32 v135, v134, v132
	v_cmp_gt_u32_e32 vcc, 16, v135
	v_sub_u32_e32 v136, v134, v131
	v_lshlrev_b32_e32 v136, 2, v136
	v_add_u32_e32 v136, 60, v136
	v_cndmask_b32_e32 v172, v210, v136, vcc
	v_add_u32_e32 v134, 17, v133
	v_sub_u32_e32 v135, v134, v132
	v_cmp_gt_u32_e32 vcc, 16, v135
	v_sub_u32_e32 v136, v134, v131
	v_lshlrev_b32_e32 v136, 2, v136
	v_add_u32_e32 v136, 60, v136
	v_cndmask_b32_e32 v173, v210, v136, vcc
	v_add_u32_e32 v134, 18, v133
	v_sub_u32_e32 v135, v134, v132
	v_cmp_gt_u32_e32 vcc, 16, v135
	v_sub_u32_e32 v136, v134, v131
	v_lshlrev_b32_e32 v136, 2, v136
	v_add_u32_e32 v136, 60, v136
	v_cndmask_b32_e32 v174, v210, v136, vcc
	v_add_u32_e32 v134, 19, v133
	v_sub_u32_e32 v135, v134, v132
	v_cmp_gt_u32_e32 vcc, 16, v135
	v_sub_u32_e32 v136, v134, v131
	v_lshlrev_b32_e32 v136, 2, v136
	v_add_u32_e32 v136, 60, v136
	v_cndmask_b32_e32 v175, v210, v136, vcc
	v_mov_b32_e32 v143, 0xf149f2ca
	v_mov_b32_e32 v137, v112
	v_lshrrev_b32_e32 v138, 5, v137
	v_and_b32_e32 v139, 31, v137
	v_mul_u32_u24_e32 v140, 31, v138
	v_add_u32_e32 v140, v140, v139
	v_min_u32_e32 v140, 0x1d0, v140
	v_lshlrev_b32_e32 v140, 2, v140
	global_load_dword v141, v140, s[12:13]
	v_lshl_add_u32 v142, v137, 2, v117
	v_add_u32_e32 v142, 0x10000, v142
	v_cmp_eq_u32_e32 vcc, 31, v139
	s_waitcnt vmcnt(0)
; __device__ __forceinline__ void attn_phase(const Params& P, char* smem_raw) {
;     ...
;   int dco[4][4];
; #pragma unroll
;   for (int reg = 0; reg < 4; ++reg) {
;     const int c = wid * 16 + (lane >> 4) * 4 + reg;
;     const int cs = min(max(c - 8, 0), 48);
; #pragma unroll
;     for (int q4 = 0; q4 < 4; ++q4) {
;       const int kc = q4 * 16 + (lane & 15);
;       dco[reg][q4] = (kc >= cs && kc < cs + 16) ? (kc - c + 15) : 465;
;     }
;   }
;   int t = VBID;
;   __syncthreads();
;   if (t < 8192) {
;     const int h0 = t & 15;
;     for (int idx = tid; idx < 930; idx += VTHR) sm_rpb[idx] = (idx < 465) ? P.rpb[h0 * 465 + idx] * 1.4426950408889634f : -1e30f;
;     ATT_ISSUE(t, 0)
;     ATT_QLOAD(t)
;   }
;   for (; t < 8192; t += VGRID) {
;     const int h = t & 15, r = (t >> 4) & 127, b = t >> 11;
;     const int rs = min(max(r - 4, 0), 120);
;     bf16x8 qf[2];
;     qf[0] = qn[0]; qf[1] = qn[1];
;     f32x4 o[4];
; #pragma unroll
;     for (int td = 0; td < 4; ++td) o[td] = f32x4{0.f, 0.f, 0.f, 0.f};
	v_mul_f32_e32 v141, 0x3fb8aa3b, v141
	v_cndmask_b32_e32 v141, v141, v143, vcc
	ds_write_b32 v142, v141
	v_add_u32_e32 v137, 0x100, v112
	v_lshrrev_b32_e32 v138, 5, v137
	v_and_b32_e32 v139, 31, v137
	v_mul_u32_u24_e32 v140, 31, v138
	v_add_u32_e32 v140, v140, v139
	v_min_u32_e32 v140, 0x1d0, v140
	v_lshlrev_b32_e32 v140, 2, v140
	global_load_dword v141, v140, s[12:13]
	v_lshl_add_u32 v142, v137, 2, v117
	v_add_u32_e32 v142, 0x10000, v142
	v_cmp_eq_u32_e32 vcc, 31, v139
	s_waitcnt vmcnt(0)
	v_mul_f32_e32 v141, 0x3fb8aa3b, v141
	v_cndmask_b32_e32 v141, v141, v143, vcc
	ds_write_b32 v142, v141
	s_and_b32 s0, s3, 0xff
	s_lshr_b32 s1, s0, 2
	s_and_b32 s0, s0, 3
	s_lshl_b32 s0, s0, 5
	s_lshr_b32 vcc_lo, s3, 12
	s_add_u32 s0, s0, vcc_lo
	s_sub_i32 vcc_lo, s0, 4
	s_max_i32 vcc_lo, vcc_lo, 0
	s_min_i32 vcc_lo, vcc_lo, 0x78
	s_lshl_b32 vcc_hi, s1, 13
	s_lshl_b32 m0, vcc_lo, 6
	s_add_u32 m0, m0, vcc_hi
	s_mul_i32 m0, m0, 0x1800
	s_add_u32 s12, s4, m0
	s_addc_u32 s13, s5, 0
	s_lshl_b32 m0, s1, 24
	s_lshl_b32 s100, vcc_lo, 7
	s_add_u32 m0, m0, s100
	s_add_u32 s14, s6, m0
	s_addc_u32 s15, s7, 0
	s_lshl_b32 m0, s0, 6
	s_add_u32 m0, m0, vcc_hi
	s_mul_i32 m0, m0, 0x1800
	s_add_u32 s100, s4, m0
	s_addc_u32 s101, s5, 0
	global_load_dwordx4 v[64:67], v166, s[100:101]
	global_load_dwordx4 v[68:71], v166, s[100:101] offset:64
	s_and_b32 s0, s3, 0xff
	s_lshr_b32 s1, s0, 2
	s_and_b32 s0, s0, 3
	s_lshl_b32 s0, s0, 5
	s_lshr_b32 vcc_lo, s3, 12
	s_add_u32 s0, s0, vcc_lo
	s_sub_i32 vcc_lo, s0, 4
	s_max_i32 vcc_lo, vcc_lo, 0
	s_min_i32 vcc_lo, vcc_lo, 0x78
	s_lshl_b32 vcc_hi, s1, 13
	s_sub_i32 vcc_lo, vcc_lo, s0
	s_add_i32 vcc_lo, vcc_lo, 4
	s_lshl_b32 vcc_lo, vcc_lo, 7
	s_bfe_u32 m0, s3, 0x10008
	s_mul_i32 m0, m0, 0x12000
	s_add_i32 vcc_lo, vcc_lo, m0
	s_add_i32 vcc_lo, vcc_lo, 0x10010
	v_add_u32_e32 v184, vcc_lo, v168
	v_add_u32_e32 v185, vcc_lo, v169
	v_add_u32_e32 v186, vcc_lo, v170
	v_add_u32_e32 v187, vcc_lo, v171
	v_add_u32_e32 v188, vcc_lo, v172
	v_add_u32_e32 v189, vcc_lo, v173
	v_add_u32_e32 v190, vcc_lo, v174
	v_add_u32_e32 v191, vcc_lo, v175
	s_add_u32 s100, s12, 0x0
	s_addc_u32 s101, s13, 0
	s_add_u32 s0, s14, 0x0
	s_addc_u32 s1, s15, 0
	global_load_dwordx4 v[80:83], v154, s[100:101] offset:2048
	global_load_dwordx4 v[96:99], v158, s[0:1]
	global_load_dwordx4 v[84:87], v155, s[100:101] offset:2048
	global_load_dwordx4 v[100:103], v159, s[0:1]
	global_load_dwordx4 v[88:91], v156, s[100:101] offset:2048
	global_load_dwordx4 v[104:107], v160, s[0:1]
	global_load_dwordx4 v[92:95], v157, s[100:101] offset:2048
	global_load_dwordx4 v[108:111], v161, s[0:1]
	v_mov_b32_e32 v200, 0xf149f2ca
	v_mov_b32_e32 v201, 0
	v_mov_b32_e32 v32, 0
	v_mov_b32_e32 v33, 0
	v_mov_b32_e32 v34, 0
	v_mov_b32_e32 v35, 0
	v_mov_b32_e32 v36, 0
	v_mov_b32_e32 v37, 0
	v_mov_b32_e32 v38, 0
	v_mov_b32_e32 v39, 0
	v_mov_b32_e32 v40, 0
	v_mov_b32_e32 v41, 0
	v_mov_b32_e32 v42, 0
	v_mov_b32_e32 v43, 0
	v_mov_b32_e32 v44, 0
	v_mov_b32_e32 v45, 0
	v_mov_b32_e32 v46, 0
	v_mov_b32_e32 v47, 0
	s_waitcnt vmcnt(0)
	ds_write_b128 v150, v[80:83] offset:0
	ds_write_b128 v150, v[84:87] offset:4096
	ds_write_b128 v150, v[88:91] offset:8192
	ds_write_b128 v150, v[92:95] offset:12288
	ds_write_b64 v151, v[96:97] offset:0
	ds_write_b64 v229, v[98:99] offset:0
	ds_write_b64 v151, v[100:101] offset:4096
	ds_write_b64 v229, v[102:103] offset:4096
	ds_write_b64 v151, v[104:105] offset:8192
	ds_write_b64 v229, v[106:107] offset:8192
	ds_write_b64 v151, v[108:109] offset:12288
	ds_write_b64 v229, v[110:111] offset:12288
	s_add_u32 s100, s12, 0xc0000
	s_addc_u32 s101, s13, 0
	s_add_u32 s0, s14, 0x100
	s_addc_u32 s1, s15, 0
	global_load_dwordx4 v[80:83], v154, s[100:101] offset:2048
	global_load_dwordx4 v[96:99], v158, s[0:1]
	global_load_dwordx4 v[84:87], v155, s[100:101] offset:2048
	global_load_dwordx4 v[100:103], v159, s[0:1]
	global_load_dwordx4 v[88:91], v156, s[100:101] offset:2048
	global_load_dwordx4 v[104:107], v160, s[0:1]
	global_load_dwordx4 v[92:95], v157, s[100:101] offset:2048
	global_load_dwordx4 v[108:111], v161, s[0:1]
	s_waitcnt lgkmcnt(0)
	s_barrier
	ds_read_b32 v0, v184 offset:384
	ds_read_b32 v1, v185 offset:384
	ds_read_b32 v2, v186 offset:384
	ds_read_b32 v3, v187 offset:384
	ds_read_b32 v4, v184 offset:512
	ds_read_b32 v5, v185 offset:512
	ds_read_b32 v6, v186 offset:512
	ds_read_b32 v7, v187 offset:512
	ds_read_b32 v8, v188 offset:384
	ds_read_b32 v9, v189 offset:384
	ds_read_b32 v10, v190 offset:384
	ds_read_b32 v11, v191 offset:384
	ds_read_b32 v12, v188 offset:512
	ds_read_b32 v13, v189 offset:512
	ds_read_b32 v14, v190 offset:512
	ds_read_b32 v15, v191 offset:512
	s_waitcnt lgkmcnt(0)
	s_waitcnt vmcnt(0)
; __device__ __forceinline__ void attn_phase(const Params& P, char* smem_raw) {
;     ...
;       f32x4 sacc[8];
; #pragma unroll
;       for (int t8 = 0; t8 < 8; ++t8) sacc[t8] = f32x4{0.f, 0.f, 0.f, 0.f};
; #pragma unroll
;       for (int s = 0; s < 2; ++s)
; #pragma unroll
;         for (int t8 = 0; t8 < 8; ++t8) {
;           const bf16x8 kf = *reinterpret_cast<const bf16x8*>(&sm_k[(t8 * 16 + (lane_c & 15)) * LDSS + s * 32 + (lane_c >> 4) * 8]);
;           sacc[t8] = __builtin_amdgcn_mfma_f32_16x16x32_bf16(qf[s], kf, sacc[t8], 0, 0, 0);
;         }
;       if (ck < 5) {
;         ATT_ISSUE(t, ck + 1)
;       } else if (t + VGRID < 8192) {
;         ATT_ISSUE(t + VGRID, 0)
;         ATT_QLOAD(t + VGRID)
;       }
;       if (ck < 4) {
;         const float* rb0 = sm_rpb + (rs + ck * 2 - r + 7) * 31;
; #pragma unroll
;         for (int t8 = 0; t8 < 8; ++t8)
; #pragma unroll
;           for (int reg = 0; reg < 4; ++reg)
;             sacc[t8][reg] += rb0[(t8 >> 2) * 31 + dco[reg][t8 & 3]];
;       }
; #pragma unroll
;       for (int reg = 0; reg < 4; ++reg) {
;         float mx = sacc[0][reg];
; #pragma unroll
;         for (int t8 = 1; t8 < 8; ++t8) mx = fmaxf(mx, sacc[t8][reg]);
;         mx = row16_max(mx);
;         const float mnew = fmaxf(mrow[reg], mx);
;         const float alpha = __builtin_amdgcn_exp2f(mrow[reg] - mnew);
;         mrow[reg] = mnew;
;         float rsum = 0.f;
; #pragma unroll
;         for (int t8 = 0; t8 < 8; ++t8) {
;           const float p = __builtin_amdgcn_exp2f(sacc[t8][reg] - mnew);
;           rsum += p;
;           sm_p[(wid * 16 + (lane_c >> 4) * 4 + reg) * 136 + t8 * 16 + (lane_c & 15)] = f2bf(p);
;         }
;         rsum = row16_sum(rsum);
;         lrow[reg] = lrow[reg] * alpha + rsum;
; #pragma unroll
;         for (int td = 0; td < 4; ++td) o[td][reg] *= alpha;
;       }
;       asm volatile("s_waitcnt lgkmcnt(0)" ::: "memory");
; #pragma unroll
;       for (int s4 = 0; s4 < 4; ++s4) {
;         const bf16x8 pf = *reinterpret_cast<const bf16x8*>(&sm_p[(wid * 16 + (lane_c & 15)) * 136 + s4 * 32 + (lane_c >> 4) * 8]);
; #pragma unroll
;         for (int td = 0; td < 4; ++td) {
;           const bf16x8 vf = *reinterpret_cast<const bf16x8*>(&sm_vt[(td * 16 + (lane_c & 15)) * 136 + s4 * 32 + (lane_c >> 4) * 8]);
;           o[td] = __builtin_amdgcn_mfma_f32_16x16x32_bf16(pf, vf, o[td], 0, 0, 0);
;         }
;       }
.Lmy_att_tile:
	s_barrier
	ds_read_b128 v[112:115], v144 offset:0
	ds_read_b128 v[116:119], v145 offset:0
	ds_read_b128 v[120:123], v144 offset:8192
	ds_read_b128 v[124:127], v145 offset:8192
	ds_read_b128 v[128:131], v144 offset:2048
	ds_read_b128 v[132:135], v145 offset:2048
	ds_read_b128 v[136:139], v144 offset:10240
	ds_read_b128 v[140:143], v145 offset:10240
	s_waitcnt lgkmcnt(7)
	v_mfma_f32_16x16x32_bf16 v[0:3], v[112:115], v[64:67], v[0:3]
	s_waitcnt lgkmcnt(6)
	v_mfma_f32_16x16x32_bf16 v[0:3], v[116:119], v[68:71], v[0:3]
	s_waitcnt lgkmcnt(5)
	v_mfma_f32_16x16x32_bf16 v[4:7], v[120:123], v[64:67], v[4:7]
	s_waitcnt lgkmcnt(4)
	v_mfma_f32_16x16x32_bf16 v[4:7], v[124:127], v[68:71], v[4:7]
	s_waitcnt lgkmcnt(3)
	v_mfma_f32_16x16x32_bf16 v[8:11], v[128:131], v[64:67], v[8:11]
	s_waitcnt lgkmcnt(2)
	v_mfma_f32_16x16x32_bf16 v[8:11], v[132:135], v[68:71], v[8:11]
	s_waitcnt lgkmcnt(1)
	v_mfma_f32_16x16x32_bf16 v[12:15], v[136:139], v[64:67], v[12:15]
	s_waitcnt lgkmcnt(0)
	v_mfma_f32_16x16x32_bf16 v[12:15], v[140:143], v[68:71], v[12:15]
	s_nop 7
	v_max3_f32 v203, v0, v1, v2
	v_max3_f32 v203, v203, v3, v4
	v_max3_f32 v203, v203, v5, v6
	v_max3_f32 v203, v203, v7, v8
	v_max3_f32 v203, v203, v9, v10
	v_max3_f32 v203, v203, v11, v12
	v_max3_f32 v203, v203, v13, v14
	v_max_f32_e32 v203, v203, v15
	v_mov_b32_e32 v205, v203
	s_nop 1
	v_permlane16_swap_b32_e32 v203, v205
	v_max_f32_e32 v203, v203, v205
	v_mov_b32_e32 v205, v203
	s_nop 1
	v_permlane32_swap_b32_e32 v203, v205
	v_max_f32_e32 v203, v203, v205
	v_max_f32_e32 v218, v200, v203
	v_sub_f32_e32 v220, v200, v218
	v_mov_b32_e32 v219, v218
	v_exp_f32_e32 v220, v220
	v_mov_b32_e32 v200, v218
	v_pk_add_f32 v[0:1], v[0:1], v[218:219] neg_lo:[0,1] neg_hi:[0,1]
	v_pk_add_f32 v[2:3], v[2:3], v[218:219] neg_lo:[0,1] neg_hi:[0,1]
	v_pk_add_f32 v[4:5], v[4:5], v[218:219] neg_lo:[0,1] neg_hi:[0,1]
	v_pk_add_f32 v[6:7], v[6:7], v[218:219] neg_lo:[0,1] neg_hi:[0,1]
	v_pk_add_f32 v[8:9], v[8:9], v[218:219] neg_lo:[0,1] neg_hi:[0,1]
	v_pk_add_f32 v[10:11], v[10:11], v[218:219] neg_lo:[0,1] neg_hi:[0,1]
	v_pk_add_f32 v[12:13], v[12:13], v[218:219] neg_lo:[0,1] neg_hi:[0,1]
	v_pk_add_f32 v[14:15], v[14:15], v[218:219] neg_lo:[0,1] neg_hi:[0,1]
	v_exp_f32_e32 v0, v0
	s_waitcnt vmcnt(4)
	v_exp_f32_e32 v1, v1
	ds_write_b128 v150, v[80:83] offset:32768
	v_exp_f32_e32 v2, v2
	ds_write_b128 v150, v[84:87] offset:36864
	v_exp_f32_e32 v3, v3
	ds_write_b128 v150, v[88:91] offset:40960
	v_exp_f32_e32 v4, v4
	ds_write_b128 v150, v[92:95] offset:45056
	v_exp_f32_e32 v5, v5
	ds_write_b64 v151, v[96:97] offset:32768
	v_exp_f32_e32 v6, v6
	ds_write_b64 v229, v[98:99] offset:32768
	v_exp_f32_e32 v7, v7
	ds_write_b64 v151, v[100:101] offset:36864
	v_exp_f32_e32 v8, v8
	ds_write_b64 v229, v[102:103] offset:36864
	v_exp_f32_e32 v9, v9
	ds_write_b64 v151, v[104:105] offset:40960
	v_exp_f32_e32 v10, v10
	ds_write_b64 v229, v[106:107] offset:40960
	v_exp_f32_e32 v11, v11
	ds_write_b64 v151, v[108:109] offset:45056
	v_exp_f32_e32 v12, v12
	ds_write_b64 v229, v[110:111] offset:45056
	v_exp_f32_e32 v13, v13
	s_add_u32 s100, s12, 0x180000
	v_exp_f32_e32 v14, v14
	s_addc_u32 s101, s13, 0
	v_exp_f32_e32 v15, v15
	s_add_u32 s0, s14, 0x200
	s_addc_u32 s1, s15, 0
	global_load_dwordx4 v[80:83], v154, s[100:101] offset:2048
	global_load_dwordx4 v[96:99], v158, s[0:1]
	global_load_dwordx4 v[84:87], v155, s[100:101] offset:2048
	global_load_dwordx4 v[100:103], v159, s[0:1]
	global_load_dwordx4 v[88:91], v156, s[100:101] offset:2048
	global_load_dwordx4 v[104:107], v160, s[0:1]
	global_load_dwordx4 v[92:95], v157, s[100:101] offset:2048
	global_load_dwordx4 v[108:111], v161, s[0:1]
	s_and_b32 s0, s3, 0xff
	s_lshr_b32 s1, s0, 2
	s_and_b32 s0, s0, 3
	s_lshl_b32 s0, s0, 5
	s_lshr_b32 vcc_lo, s3, 12
	s_add_u32 s0, s0, vcc_lo
	s_sub_i32 vcc_lo, s0, 4
	s_max_i32 vcc_lo, vcc_lo, 0
	s_min_i32 vcc_lo, vcc_lo, 0x78
	s_lshl_b32 vcc_hi, s1, 13
	s_lshl_b32 m0, s1, 8
	s_add_u32 m0, m0, 0x8000
	s_mul_i32 m0, m0, 0x1800
	s_add_u32 s16, s4, m0
	s_addc_u32 s17, s5, 0
	s_lshl_b32 m0, s1, 19
	s_add_u32 s36, s8, m0
	s_addc_u32 s37, s9, 0
	s_lshl_b32 m0, s0, 6
	s_add_u32 m0, m0, vcc_hi
	s_lshl_b32 m0, m0, 11
	s_add_u32 s98, s10, m0
	s_addc_u32 s99, s11, 0
	ds_read_b128 v[112:115], v146 offset:0
	ds_read_b128 v[116:119], v146 offset:4096
	ds_read_b128 v[120:123], v146 offset:8192
	ds_read_b128 v[124:127], v146 offset:12288
	ds_read_b128 v[128:131], v147 offset:0
	ds_read_b128 v[132:135], v147 offset:4096
	ds_read_b128 v[136:139], v147 offset:8192
	ds_read_b128 v[140:143], v147 offset:12288
	v_mov_b32_e32 v221, v220
	v_pk_add_f32 v[222:223], v[0:1], v[2:3]
	v_pk_add_f32 v[222:223], v[222:223], v[4:5]
	v_pk_add_f32 v[222:223], v[222:223], v[6:7]
	v_pk_add_f32 v[222:223], v[222:223], v[8:9]
	v_pk_add_f32 v[222:223], v[222:223], v[10:11]
	v_pk_add_f32 v[222:223], v[222:223], v[12:13]
	v_pk_add_f32 v[222:223], v[222:223], v[14:15]
	v_pk_mul_f32 v[32:33], v[32:33], v[220:221]
	v_pk_mul_f32 v[34:35], v[34:35], v[220:221]
	v_pk_mul_f32 v[36:37], v[36:37], v[220:221]
	v_pk_mul_f32 v[38:39], v[38:39], v[220:221]
	v_pk_mul_f32 v[40:41], v[40:41], v[220:221]
	v_pk_mul_f32 v[42:43], v[42:43], v[220:221]
	v_pk_mul_f32 v[44:45], v[44:45], v[220:221]
	v_pk_mul_f32 v[46:47], v[46:47], v[220:221]
	v_add_f32_e32 v203, v222, v223
	v_fma_f32 v201, v201, v220, v203
	v_cvt_pk_bf16_f32 v48, v0, v1
	v_cvt_pk_bf16_f32 v49, v2, v3
	v_cvt_pk_bf16_f32 v50, v4, v5
	v_cvt_pk_bf16_f32 v51, v6, v7
	v_cvt_pk_bf16_f32 v52, v8, v9
	v_cvt_pk_bf16_f32 v53, v10, v11
	v_cvt_pk_bf16_f32 v54, v12, v13
	v_cvt_pk_bf16_f32 v55, v14, v15
	s_waitcnt lgkmcnt(7)
	v_mfma_f32_16x16x32_bf16 v[32:35], v[112:115], v[48:51], v[32:35]
	s_waitcnt lgkmcnt(6)
	v_mfma_f32_16x16x32_bf16 v[36:39], v[116:119], v[48:51], v[36:39]
	s_waitcnt lgkmcnt(5)
	v_mfma_f32_16x16x32_bf16 v[40:43], v[120:123], v[48:51], v[40:43]
	s_waitcnt lgkmcnt(4)
	v_mfma_f32_16x16x32_bf16 v[44:47], v[124:127], v[48:51], v[44:47]
	s_waitcnt lgkmcnt(3)
	v_mfma_f32_16x16x32_bf16 v[32:35], v[128:131], v[52:55], v[32:35]
	s_waitcnt lgkmcnt(2)
	v_mfma_f32_16x16x32_bf16 v[36:39], v[132:135], v[52:55], v[36:39]
	s_waitcnt lgkmcnt(1)
	v_mfma_f32_16x16x32_bf16 v[40:43], v[136:139], v[52:55], v[40:43]
	s_waitcnt lgkmcnt(0)
	v_mfma_f32_16x16x32_bf16 v[44:47], v[140:143], v[52:55], v[44:47]
	ds_read_b32 v0, v184 offset:640
	ds_read_b32 v1, v185 offset:640
	ds_read_b32 v2, v186 offset:640
	ds_read_b32 v3, v187 offset:640
	ds_read_b32 v4, v184 offset:768
	ds_read_b32 v5, v185 offset:768
	ds_read_b32 v6, v186 offset:768
	ds_read_b32 v7, v187 offset:768
	ds_read_b32 v8, v188 offset:640
	ds_read_b32 v9, v189 offset:640
	ds_read_b32 v10, v190 offset:640
	ds_read_b32 v11, v191 offset:640
	ds_read_b32 v12, v188 offset:768
	ds_read_b32 v13, v189 offset:768
	ds_read_b32 v14, v190 offset:768
	ds_read_b32 v15, v191 offset:768
	s_waitcnt lgkmcnt(0)
	s_barrier
; __device__ __forceinline__ void attn_phase(const Params& P, char* smem_raw) {
;     ...
;       f32x4 sacc[8];
; #pragma unroll
;       for (int t8 = 0; t8 < 8; ++t8) sacc[t8] = f32x4{0.f, 0.f, 0.f, 0.f};
; #pragma unroll
;       for (int s = 0; s < 2; ++s)
; #pragma unroll
;         for (int t8 = 0; t8 < 8; ++t8) {
;           const bf16x8 kf = *reinterpret_cast<const bf16x8*>(&sm_k[(t8 * 16 + (lane_c & 15)) * LDSS + s * 32 + (lane_c >> 4) * 8]);
;           sacc[t8] = __builtin_amdgcn_mfma_f32_16x16x32_bf16(qf[s], kf, sacc[t8], 0, 0, 0);
;         }
;       if (ck < 5) {
;         ATT_ISSUE(t, ck + 1)
;       } else if (t + VGRID < 8192) {
;         ATT_ISSUE(t + VGRID, 0)
;         ATT_QLOAD(t + VGRID)
;       }
;       if (ck < 4) {
;         const float* rb0 = sm_rpb + (rs + ck * 2 - r + 7) * 31;
; #pragma unroll
;         for (int t8 = 0; t8 < 8; ++t8)
; #pragma unroll
;           for (int reg = 0; reg < 4; ++reg)
;             sacc[t8][reg] += rb0[(t8 >> 2) * 31 + dco[reg][t8 & 3]];
;       }
; #pragma unroll
;       for (int reg = 0; reg < 4; ++reg) {
;         float mx = sacc[0][reg];
; #pragma unroll
;         for (int t8 = 1; t8 < 8; ++t8) mx = fmaxf(mx, sacc[t8][reg]);
;         mx = row16_max(mx);
;         const float mnew = fmaxf(mrow[reg], mx);
;         const float alpha = __builtin_amdgcn_exp2f(mrow[reg] - mnew);
;         mrow[reg] = mnew;
;         float rsum = 0.f;
; #pragma unroll
;         for (int t8 = 0; t8 < 8; ++t8) {
;           const float p = __builtin_amdgcn_exp2f(sacc[t8][reg] - mnew);
;           rsum += p;
;           sm_p[(wid * 16 + (lane_c >> 4) * 4 + reg) * 136 + t8 * 16 + (lane_c & 15)] = f2bf(p);
;         }
;         rsum = row16_sum(rsum);
;         lrow[reg] = lrow[reg] * alpha + rsum;
; #pragma unroll
;         for (int td = 0; td < 4; ++td) o[td][reg] *= alpha;
;       }
;       asm volatile("s_waitcnt lgkmcnt(0)" ::: "memory");
; #pragma unroll
;       for (int s4 = 0; s4 < 4; ++s4) {
;         const bf16x8 pf = *reinterpret_cast<const bf16x8*>(&sm_p[(wid * 16 + (lane_c & 15)) * 136 + s4 * 32 + (lane_c >> 4) * 8]);
; #pragma unroll
;         for (int td = 0; td < 4; ++td) {
;           const bf16x8 vf = *reinterpret_cast<const bf16x8*>(&sm_vt[(td * 16 + (lane_c & 15)) * 136 + s4 * 32 + (lane_c >> 4) * 8]);
;           o[td] = __builtin_amdgcn_mfma_f32_16x16x32_bf16(pf, vf, o[td], 0, 0, 0);
;         }
;       }
	ds_read_b128 v[112:115], v144 offset:32768
	ds_read_b128 v[116:119], v145 offset:32768
	ds_read_b128 v[120:123], v144 offset:40960
	ds_read_b128 v[124:127], v145 offset:40960
	ds_read_b128 v[128:131], v144 offset:34816
	ds_read_b128 v[132:135], v145 offset:34816
	ds_read_b128 v[136:139], v144 offset:43008
	ds_read_b128 v[140:143], v145 offset:43008
	s_waitcnt lgkmcnt(7)
	v_mfma_f32_16x16x32_bf16 v[0:3], v[112:115], v[64:67], v[0:3]
	s_waitcnt lgkmcnt(6)
	v_mfma_f32_16x16x32_bf16 v[0:3], v[116:119], v[68:71], v[0:3]
	s_waitcnt lgkmcnt(5)
	v_mfma_f32_16x16x32_bf16 v[4:7], v[120:123], v[64:67], v[4:7]
	s_waitcnt lgkmcnt(4)
	v_mfma_f32_16x16x32_bf16 v[4:7], v[124:127], v[68:71], v[4:7]
	s_waitcnt lgkmcnt(3)
	v_mfma_f32_16x16x32_bf16 v[8:11], v[128:131], v[64:67], v[8:11]
	s_waitcnt lgkmcnt(2)
	v_mfma_f32_16x16x32_bf16 v[8:11], v[132:135], v[68:71], v[8:11]
	s_waitcnt lgkmcnt(1)
	v_mfma_f32_16x16x32_bf16 v[12:15], v[136:139], v[64:67], v[12:15]
	s_waitcnt lgkmcnt(0)
	v_mfma_f32_16x16x32_bf16 v[12:15], v[140:143], v[68:71], v[12:15]
	s_nop 7
	v_max3_f32 v203, v0, v1, v2
	v_max3_f32 v203, v203, v3, v4
	v_max3_f32 v203, v203, v5, v6
	v_max3_f32 v203, v203, v7, v8
	v_max3_f32 v203, v203, v9, v10
	v_max3_f32 v203, v203, v11, v12
	v_max3_f32 v203, v203, v13, v14
	v_max_f32_e32 v203, v203, v15
	v_mov_b32_e32 v205, v203
	s_nop 1
	v_permlane16_swap_b32_e32 v203, v205
	v_max_f32_e32 v203, v203, v205
	v_mov_b32_e32 v205, v203
	s_nop 1
	v_permlane32_swap_b32_e32 v203, v205
	v_max_f32_e32 v203, v203, v205
	v_max_f32_e32 v218, v200, v203
	v_sub_f32_e32 v220, v200, v218
	v_mov_b32_e32 v219, v218
	v_exp_f32_e32 v220, v220
	v_mov_b32_e32 v200, v218
	v_pk_add_f32 v[0:1], v[0:1], v[218:219] neg_lo:[0,1] neg_hi:[0,1]
	v_pk_add_f32 v[2:3], v[2:3], v[218:219] neg_lo:[0,1] neg_hi:[0,1]
	v_pk_add_f32 v[4:5], v[4:5], v[218:219] neg_lo:[0,1] neg_hi:[0,1]
	v_pk_add_f32 v[6:7], v[6:7], v[218:219] neg_lo:[0,1] neg_hi:[0,1]
	v_pk_add_f32 v[8:9], v[8:9], v[218:219] neg_lo:[0,1] neg_hi:[0,1]
	v_pk_add_f32 v[10:11], v[10:11], v[218:219] neg_lo:[0,1] neg_hi:[0,1]
	v_pk_add_f32 v[12:13], v[12:13], v[218:219] neg_lo:[0,1] neg_hi:[0,1]
	v_pk_add_f32 v[14:15], v[14:15], v[218:219] neg_lo:[0,1] neg_hi:[0,1]
	v_exp_f32_e32 v0, v0
	s_waitcnt vmcnt(0)
	v_exp_f32_e32 v1, v1
	ds_write_b128 v150, v[80:83] offset:0
	v_exp_f32_e32 v2, v2
	ds_write_b128 v150, v[84:87] offset:4096
	v_exp_f32_e32 v3, v3
	ds_write_b128 v150, v[88:91] offset:8192
	v_exp_f32_e32 v4, v4
	ds_write_b128 v150, v[92:95] offset:12288
	v_exp_f32_e32 v5, v5
	ds_write_b64 v151, v[96:97] offset:0
	v_exp_f32_e32 v6, v6
	ds_write_b64 v229, v[98:99] offset:0
	v_exp_f32_e32 v7, v7
	ds_write_b64 v151, v[100:101] offset:4096
	v_exp_f32_e32 v8, v8
	ds_write_b64 v229, v[102:103] offset:4096
	v_exp_f32_e32 v9, v9
	ds_write_b64 v151, v[104:105] offset:8192
	v_exp_f32_e32 v10, v10
	ds_write_b64 v229, v[106:107] offset:8192
	v_exp_f32_e32 v11, v11
	ds_write_b64 v151, v[108:109] offset:12288
	v_exp_f32_e32 v12, v12
	ds_write_b64 v229, v[110:111] offset:12288
	v_exp_f32_e32 v13, v13
	s_add_u32 s100, s12, 0x240000
	v_exp_f32_e32 v14, v14
	s_addc_u32 s101, s13, 0
	v_exp_f32_e32 v15, v15
	s_add_u32 s0, s14, 0x300
	s_addc_u32 s1, s15, 0
	global_load_dwordx4 v[80:83], v154, s[100:101] offset:2048
	global_load_dwordx4 v[96:99], v158, s[0:1]
	global_load_dwordx4 v[84:87], v155, s[100:101] offset:2048
	global_load_dwordx4 v[100:103], v159, s[0:1]
	global_load_dwordx4 v[88:91], v156, s[100:101] offset:2048
	global_load_dwordx4 v[104:107], v160, s[0:1]
	global_load_dwordx4 v[92:95], v157, s[100:101] offset:2048
	global_load_dwordx4 v[108:111], v161, s[0:1]
	ds_read_b128 v[112:115], v146 offset:32768
	ds_read_b128 v[116:119], v146 offset:36864
	ds_read_b128 v[120:123], v146 offset:40960
	ds_read_b128 v[124:127], v146 offset:45056
	ds_read_b128 v[128:131], v147 offset:32768
	ds_read_b128 v[132:135], v147 offset:36864
	ds_read_b128 v[136:139], v147 offset:40960
	ds_read_b128 v[140:143], v147 offset:45056
	v_mov_b32_e32 v221, v220
	v_pk_add_f32 v[222:223], v[0:1], v[2:3]
	v_pk_add_f32 v[222:223], v[222:223], v[4:5]
	v_pk_add_f32 v[222:223], v[222:223], v[6:7]
	v_pk_add_f32 v[222:223], v[222:223], v[8:9]
	v_pk_add_f32 v[222:223], v[222:223], v[10:11]
	v_pk_add_f32 v[222:223], v[222:223], v[12:13]
	v_pk_add_f32 v[222:223], v[222:223], v[14:15]
	v_pk_mul_f32 v[32:33], v[32:33], v[220:221]
	v_pk_mul_f32 v[34:35], v[34:35], v[220:221]
	v_pk_mul_f32 v[36:37], v[36:37], v[220:221]
	v_pk_mul_f32 v[38:39], v[38:39], v[220:221]
	v_pk_mul_f32 v[40:41], v[40:41], v[220:221]
	v_pk_mul_f32 v[42:43], v[42:43], v[220:221]
	v_pk_mul_f32 v[44:45], v[44:45], v[220:221]
	v_pk_mul_f32 v[46:47], v[46:47], v[220:221]
	v_add_f32_e32 v203, v222, v223
	v_fma_f32 v201, v201, v220, v203
	v_cvt_pk_bf16_f32 v48, v0, v1
	v_cvt_pk_bf16_f32 v49, v2, v3
	v_cvt_pk_bf16_f32 v50, v4, v5
	v_cvt_pk_bf16_f32 v51, v6, v7
	v_cvt_pk_bf16_f32 v52, v8, v9
	v_cvt_pk_bf16_f32 v53, v10, v11
	v_cvt_pk_bf16_f32 v54, v12, v13
	v_cvt_pk_bf16_f32 v55, v14, v15
	s_waitcnt lgkmcnt(7)
	v_mfma_f32_16x16x32_bf16 v[32:35], v[112:115], v[48:51], v[32:35]
	s_waitcnt lgkmcnt(6)
	v_mfma_f32_16x16x32_bf16 v[36:39], v[116:119], v[48:51], v[36:39]
	s_waitcnt lgkmcnt(5)
	v_mfma_f32_16x16x32_bf16 v[40:43], v[120:123], v[48:51], v[40:43]
	s_waitcnt lgkmcnt(4)
	v_mfma_f32_16x16x32_bf16 v[44:47], v[124:127], v[48:51], v[44:47]
	s_waitcnt lgkmcnt(3)
	v_mfma_f32_16x16x32_bf16 v[32:35], v[128:131], v[52:55], v[32:35]
	s_waitcnt lgkmcnt(2)
	v_mfma_f32_16x16x32_bf16 v[36:39], v[132:135], v[52:55], v[36:39]
	s_waitcnt lgkmcnt(1)
	v_mfma_f32_16x16x32_bf16 v[40:43], v[136:139], v[52:55], v[40:43]
	s_waitcnt lgkmcnt(0)
	v_mfma_f32_16x16x32_bf16 v[44:47], v[140:143], v[52:55], v[44:47]
	ds_read_b32 v0, v184 offset:896
	ds_read_b32 v1, v185 offset:896
	ds_read_b32 v2, v186 offset:896
	ds_read_b32 v3, v187 offset:896
	ds_read_b32 v4, v184 offset:1024
	ds_read_b32 v5, v185 offset:1024
	ds_read_b32 v6, v186 offset:1024
	ds_read_b32 v7, v187 offset:1024
	ds_read_b32 v8, v188 offset:896
	ds_read_b32 v9, v189 offset:896
	ds_read_b32 v10, v190 offset:896
	ds_read_b32 v11, v191 offset:896
	ds_read_b32 v12, v188 offset:1024
	ds_read_b32 v13, v189 offset:1024
	ds_read_b32 v14, v190 offset:1024
	ds_read_b32 v15, v191 offset:1024
	s_waitcnt lgkmcnt(0)
	s_barrier
; __device__ __forceinline__ void attn_phase(const Params& P, char* smem_raw) {
;     ...
;       f32x4 sacc[8];
; #pragma unroll
;       for (int t8 = 0; t8 < 8; ++t8) sacc[t8] = f32x4{0.f, 0.f, 0.f, 0.f};
; #pragma unroll
;       for (int s = 0; s < 2; ++s)
; #pragma unroll
;         for (int t8 = 0; t8 < 8; ++t8) {
;           const bf16x8 kf = *reinterpret_cast<const bf16x8*>(&sm_k[(t8 * 16 + (lane_c & 15)) * LDSS + s * 32 + (lane_c >> 4) * 8]);
;           sacc[t8] = __builtin_amdgcn_mfma_f32_16x16x32_bf16(qf[s], kf, sacc[t8], 0, 0, 0);
;         }
;       if (ck < 5) {
;         ATT_ISSUE(t, ck + 1)
;       } else if (t + VGRID < 8192) {
;         ATT_ISSUE(t + VGRID, 0)
;         ATT_QLOAD(t + VGRID)
;       }
;       if (ck < 4) {
;         const float* rb0 = sm_rpb + (rs + ck * 2 - r + 7) * 31;
; #pragma unroll
;         for (int t8 = 0; t8 < 8; ++t8)
; #pragma unroll
;           for (int reg = 0; reg < 4; ++reg)
;             sacc[t8][reg] += rb0[(t8 >> 2) * 31 + dco[reg][t8 & 3]];
;       }
; #pragma unroll
;       for (int reg = 0; reg < 4; ++reg) {
;         float mx = sacc[0][reg];
; #pragma unroll
;         for (int t8 = 1; t8 < 8; ++t8) mx = fmaxf(mx, sacc[t8][reg]);
;         mx = row16_max(mx);
;         const float mnew = fmaxf(mrow[reg], mx);
;         const float alpha = __builtin_amdgcn_exp2f(mrow[reg] - mnew);
;         mrow[reg] = mnew;
;         float rsum = 0.f;
; #pragma unroll
;         for (int t8 = 0; t8 < 8; ++t8) {
;           const float p = __builtin_amdgcn_exp2f(sacc[t8][reg] - mnew);
;           rsum += p;
;           sm_p[(wid * 16 + (lane_c >> 4) * 4 + reg) * 136 + t8 * 16 + (lane_c & 15)] = f2bf(p);
;         }
;         rsum = row16_sum(rsum);
;         lrow[reg] = lrow[reg] * alpha + rsum;
; #pragma unroll
;         for (int td = 0; td < 4; ++td) o[td][reg] *= alpha;
;       }
;       asm volatile("s_waitcnt lgkmcnt(0)" ::: "memory");
; #pragma unroll
;       for (int s4 = 0; s4 < 4; ++s4) {
;         const bf16x8 pf = *reinterpret_cast<const bf16x8*>(&sm_p[(wid * 16 + (lane_c & 15)) * 136 + s4 * 32 + (lane_c >> 4) * 8]);
; #pragma unroll
;         for (int td = 0; td < 4; ++td) {
;           const bf16x8 vf = *reinterpret_cast<const bf16x8*>(&sm_vt[(td * 16 + (lane_c & 15)) * 136 + s4 * 32 + (lane_c >> 4) * 8]);
;           o[td] = __builtin_amdgcn_mfma_f32_16x16x32_bf16(pf, vf, o[td], 0, 0, 0);
;         }
;       }
	ds_read_b128 v[112:115], v144 offset:0
	ds_read_b128 v[116:119], v145 offset:0
	ds_read_b128 v[120:123], v144 offset:8192
	ds_read_b128 v[124:127], v145 offset:8192
	ds_read_b128 v[128:131], v144 offset:2048
	ds_read_b128 v[132:135], v145 offset:2048
	ds_read_b128 v[136:139], v144 offset:10240
	ds_read_b128 v[140:143], v145 offset:10240
	s_waitcnt lgkmcnt(7)
	v_mfma_f32_16x16x32_bf16 v[0:3], v[112:115], v[64:67], v[0:3]
	s_waitcnt lgkmcnt(6)
	v_mfma_f32_16x16x32_bf16 v[0:3], v[116:119], v[68:71], v[0:3]
	s_waitcnt lgkmcnt(5)
	v_mfma_f32_16x16x32_bf16 v[4:7], v[120:123], v[64:67], v[4:7]
	s_waitcnt lgkmcnt(4)
	v_mfma_f32_16x16x32_bf16 v[4:7], v[124:127], v[68:71], v[4:7]
	s_waitcnt lgkmcnt(3)
	v_mfma_f32_16x16x32_bf16 v[8:11], v[128:131], v[64:67], v[8:11]
	s_waitcnt lgkmcnt(2)
	v_mfma_f32_16x16x32_bf16 v[8:11], v[132:135], v[68:71], v[8:11]
	s_waitcnt lgkmcnt(1)
	v_mfma_f32_16x16x32_bf16 v[12:15], v[136:139], v[64:67], v[12:15]
	s_waitcnt lgkmcnt(0)
	v_mfma_f32_16x16x32_bf16 v[12:15], v[140:143], v[68:71], v[12:15]
	s_nop 7
	v_max3_f32 v203, v0, v1, v2
	v_max3_f32 v203, v203, v3, v4
	v_max3_f32 v203, v203, v5, v6
	v_max3_f32 v203, v203, v7, v8
	v_max3_f32 v203, v203, v9, v10
	v_max3_f32 v203, v203, v11, v12
	v_max3_f32 v203, v203, v13, v14
	v_max_f32_e32 v203, v203, v15
	v_mov_b32_e32 v205, v203
	s_nop 1
	v_permlane16_swap_b32_e32 v203, v205
	v_max_f32_e32 v203, v203, v205
	v_mov_b32_e32 v205, v203
	s_nop 1
	v_permlane32_swap_b32_e32 v203, v205
	v_max_f32_e32 v203, v203, v205
	v_max_f32_e32 v218, v200, v203
	v_sub_f32_e32 v220, v200, v218
	v_mov_b32_e32 v219, v218
	v_exp_f32_e32 v220, v220
	v_mov_b32_e32 v200, v218
	v_pk_add_f32 v[0:1], v[0:1], v[218:219] neg_lo:[0,1] neg_hi:[0,1]
	v_pk_add_f32 v[2:3], v[2:3], v[218:219] neg_lo:[0,1] neg_hi:[0,1]
	v_pk_add_f32 v[4:5], v[4:5], v[218:219] neg_lo:[0,1] neg_hi:[0,1]
	v_pk_add_f32 v[6:7], v[6:7], v[218:219] neg_lo:[0,1] neg_hi:[0,1]
	v_pk_add_f32 v[8:9], v[8:9], v[218:219] neg_lo:[0,1] neg_hi:[0,1]
	v_pk_add_f32 v[10:11], v[10:11], v[218:219] neg_lo:[0,1] neg_hi:[0,1]
	v_pk_add_f32 v[12:13], v[12:13], v[218:219] neg_lo:[0,1] neg_hi:[0,1]
	v_pk_add_f32 v[14:15], v[14:15], v[218:219] neg_lo:[0,1] neg_hi:[0,1]
	v_exp_f32_e32 v0, v0
	s_waitcnt vmcnt(0)
	v_exp_f32_e32 v1, v1
	ds_write_b128 v150, v[80:83] offset:32768
	v_exp_f32_e32 v2, v2
	ds_write_b128 v150, v[84:87] offset:36864
	v_exp_f32_e32 v3, v3
	ds_write_b128 v150, v[88:91] offset:40960
	v_exp_f32_e32 v4, v4
	ds_write_b128 v150, v[92:95] offset:45056
	v_exp_f32_e32 v5, v5
	ds_write_b64 v151, v[96:97] offset:32768
	v_exp_f32_e32 v6, v6
	ds_write_b64 v229, v[98:99] offset:32768
	v_exp_f32_e32 v7, v7
	ds_write_b64 v151, v[100:101] offset:36864
	v_exp_f32_e32 v8, v8
	ds_write_b64 v229, v[102:103] offset:36864
	v_exp_f32_e32 v9, v9
	ds_write_b64 v151, v[104:105] offset:40960
	v_exp_f32_e32 v10, v10
	ds_write_b64 v229, v[106:107] offset:40960
	v_exp_f32_e32 v11, v11
	ds_write_b64 v151, v[108:109] offset:45056
	v_exp_f32_e32 v12, v12
	ds_write_b64 v229, v[110:111] offset:45056
	v_exp_f32_e32 v13, v13
	s_add_u32 s100, s16, 0x0
	v_exp_f32_e32 v14, v14
	s_addc_u32 s101, s17, 0
	v_exp_f32_e32 v15, v15
	s_add_u32 s0, s36, 0x0
	s_addc_u32 s1, s37, 0
	global_load_dwordx4 v[80:83], v154, s[100:101] offset:2048
	global_load_dwordx4 v[96:99], v162, s[0:1]
	global_load_dwordx4 v[84:87], v155, s[100:101] offset:2048
	global_load_dwordx4 v[100:103], v163, s[0:1]
	global_load_dwordx4 v[88:91], v156, s[100:101] offset:2048
	global_load_dwordx4 v[104:107], v164, s[0:1]
	global_load_dwordx4 v[92:95], v157, s[100:101] offset:2048
	global_load_dwordx4 v[108:111], v165, s[0:1]
	ds_read_b128 v[112:115], v146 offset:0
	ds_read_b128 v[116:119], v146 offset:4096
	ds_read_b128 v[120:123], v146 offset:8192
	ds_read_b128 v[124:127], v146 offset:12288
	ds_read_b128 v[128:131], v147 offset:0
	ds_read_b128 v[132:135], v147 offset:4096
	ds_read_b128 v[136:139], v147 offset:8192
	ds_read_b128 v[140:143], v147 offset:12288
	v_mov_b32_e32 v221, v220
	v_pk_add_f32 v[222:223], v[0:1], v[2:3]
	v_pk_add_f32 v[222:223], v[222:223], v[4:5]
	v_pk_add_f32 v[222:223], v[222:223], v[6:7]
	v_pk_add_f32 v[222:223], v[222:223], v[8:9]
	v_pk_add_f32 v[222:223], v[222:223], v[10:11]
	v_pk_add_f32 v[222:223], v[222:223], v[12:13]
	v_pk_add_f32 v[222:223], v[222:223], v[14:15]
	v_pk_mul_f32 v[32:33], v[32:33], v[220:221]
	v_pk_mul_f32 v[34:35], v[34:35], v[220:221]
	v_pk_mul_f32 v[36:37], v[36:37], v[220:221]
	v_pk_mul_f32 v[38:39], v[38:39], v[220:221]
	v_pk_mul_f32 v[40:41], v[40:41], v[220:221]
	v_pk_mul_f32 v[42:43], v[42:43], v[220:221]
	v_pk_mul_f32 v[44:45], v[44:45], v[220:221]
	v_pk_mul_f32 v[46:47], v[46:47], v[220:221]
	v_add_f32_e32 v203, v222, v223
	v_fma_f32 v201, v201, v220, v203
	v_cvt_pk_bf16_f32 v48, v0, v1
	v_cvt_pk_bf16_f32 v49, v2, v3
	v_cvt_pk_bf16_f32 v50, v4, v5
	v_cvt_pk_bf16_f32 v51, v6, v7
	v_cvt_pk_bf16_f32 v52, v8, v9
	v_cvt_pk_bf16_f32 v53, v10, v11
	v_cvt_pk_bf16_f32 v54, v12, v13
	v_cvt_pk_bf16_f32 v55, v14, v15
	s_waitcnt lgkmcnt(7)
	v_mfma_f32_16x16x32_bf16 v[32:35], v[112:115], v[48:51], v[32:35]
	s_waitcnt lgkmcnt(6)
	v_mfma_f32_16x16x32_bf16 v[36:39], v[116:119], v[48:51], v[36:39]
	s_waitcnt lgkmcnt(5)
	v_mfma_f32_16x16x32_bf16 v[40:43], v[120:123], v[48:51], v[40:43]
	s_waitcnt lgkmcnt(4)
	v_mfma_f32_16x16x32_bf16 v[44:47], v[124:127], v[48:51], v[44:47]
	s_waitcnt lgkmcnt(3)
	v_mfma_f32_16x16x32_bf16 v[32:35], v[128:131], v[52:55], v[32:35]
	s_waitcnt lgkmcnt(2)
	v_mfma_f32_16x16x32_bf16 v[36:39], v[132:135], v[52:55], v[36:39]
	s_waitcnt lgkmcnt(1)
	v_mfma_f32_16x16x32_bf16 v[40:43], v[136:139], v[52:55], v[40:43]
	s_waitcnt lgkmcnt(0)
	v_mfma_f32_16x16x32_bf16 v[44:47], v[140:143], v[52:55], v[44:47]
	ds_read_b32 v0, v184 offset:1152
	ds_read_b32 v1, v185 offset:1152
	ds_read_b32 v2, v186 offset:1152
	ds_read_b32 v3, v187 offset:1152
	ds_read_b32 v4, v184 offset:1280
	ds_read_b32 v5, v185 offset:1280
	ds_read_b32 v6, v186 offset:1280
	ds_read_b32 v7, v187 offset:1280
	ds_read_b32 v8, v188 offset:1152
	ds_read_b32 v9, v189 offset:1152
	ds_read_b32 v10, v190 offset:1152
	ds_read_b32 v11, v191 offset:1152
	ds_read_b32 v12, v188 offset:1280
	ds_read_b32 v13, v189 offset:1280
	ds_read_b32 v14, v190 offset:1280
	ds_read_b32 v15, v191 offset:1280
	s_waitcnt lgkmcnt(0)
	s_barrier
; __device__ __forceinline__ void attn_phase(const Params& P, char* smem_raw) {
;     ...
;       f32x4 sacc[8];
; #pragma unroll
;       for (int t8 = 0; t8 < 8; ++t8) sacc[t8] = f32x4{0.f, 0.f, 0.f, 0.f};
; #pragma unroll
;       for (int s = 0; s < 2; ++s)
; #pragma unroll
;         for (int t8 = 0; t8 < 8; ++t8) {
;           const bf16x8 kf = *reinterpret_cast<const bf16x8*>(&sm_k[(t8 * 16 + (lane_c & 15)) * LDSS + s * 32 + (lane_c >> 4) * 8]);
;           sacc[t8] = __builtin_amdgcn_mfma_f32_16x16x32_bf16(qf[s], kf, sacc[t8], 0, 0, 0);
;         }
;       if (ck < 5) {
;         ATT_ISSUE(t, ck + 1)
;       } else if (t + VGRID < 8192) {
;         ATT_ISSUE(t + VGRID, 0)
;         ATT_QLOAD(t + VGRID)
;       }
;       if (ck < 4) {
;         const float* rb0 = sm_rpb + (rs + ck * 2 - r + 7) * 31;
; #pragma unroll
;         for (int t8 = 0; t8 < 8; ++t8)
; #pragma unroll
;           for (int reg = 0; reg < 4; ++reg)
;             sacc[t8][reg] += rb0[(t8 >> 2) * 31 + dco[reg][t8 & 3]];
;       }
; #pragma unroll
;       for (int reg = 0; reg < 4; ++reg) {
;         float mx = sacc[0][reg];
; #pragma unroll
;         for (int t8 = 1; t8 < 8; ++t8) mx = fmaxf(mx, sacc[t8][reg]);
;         mx = row16_max(mx);
;         const float mnew = fmaxf(mrow[reg], mx);
;         const float alpha = __builtin_amdgcn_exp2f(mrow[reg] - mnew);
;         mrow[reg] = mnew;
;         float rsum = 0.f;
; #pragma unroll
;         for (int t8 = 0; t8 < 8; ++t8) {
;           const float p = __builtin_amdgcn_exp2f(sacc[t8][reg] - mnew);
;           rsum += p;
;           sm_p[(wid * 16 + (lane_c >> 4) * 4 + reg) * 136 + t8 * 16 + (lane_c & 15)] = f2bf(p);
;         }
;         rsum = row16_sum(rsum);
;         lrow[reg] = lrow[reg] * alpha + rsum;
; #pragma unroll
;         for (int td = 0; td < 4; ++td) o[td][reg] *= alpha;
;       }
;       asm volatile("s_waitcnt lgkmcnt(0)" ::: "memory");
; #pragma unroll
;       for (int s4 = 0; s4 < 4; ++s4) {
;         const bf16x8 pf = *reinterpret_cast<const bf16x8*>(&sm_p[(wid * 16 + (lane_c & 15)) * 136 + s4 * 32 + (lane_c >> 4) * 8]);
; #pragma unroll
;         for (int td = 0; td < 4; ++td) {
;           const bf16x8 vf = *reinterpret_cast<const bf16x8*>(&sm_vt[(td * 16 + (lane_c & 15)) * 136 + s4 * 32 + (lane_c >> 4) * 8]);
;           o[td] = __builtin_amdgcn_mfma_f32_16x16x32_bf16(pf, vf, o[td], 0, 0, 0);
;         }
;       }
	ds_read_b128 v[112:115], v144 offset:32768
	ds_read_b128 v[116:119], v145 offset:32768
	ds_read_b128 v[120:123], v144 offset:40960
	ds_read_b128 v[124:127], v145 offset:40960
	ds_read_b128 v[128:131], v144 offset:34816
	ds_read_b128 v[132:135], v145 offset:34816
	ds_read_b128 v[136:139], v144 offset:43008
	ds_read_b128 v[140:143], v145 offset:43008
	s_waitcnt lgkmcnt(7)
	v_mfma_f32_16x16x32_bf16 v[0:3], v[112:115], v[64:67], v[0:3]
	s_waitcnt lgkmcnt(6)
	v_mfma_f32_16x16x32_bf16 v[0:3], v[116:119], v[68:71], v[0:3]
	s_waitcnt lgkmcnt(5)
	v_mfma_f32_16x16x32_bf16 v[4:7], v[120:123], v[64:67], v[4:7]
	s_waitcnt lgkmcnt(4)
	v_mfma_f32_16x16x32_bf16 v[4:7], v[124:127], v[68:71], v[4:7]
	s_waitcnt lgkmcnt(3)
	v_mfma_f32_16x16x32_bf16 v[8:11], v[128:131], v[64:67], v[8:11]
	s_waitcnt lgkmcnt(2)
	v_mfma_f32_16x16x32_bf16 v[8:11], v[132:135], v[68:71], v[8:11]
	s_waitcnt lgkmcnt(1)
	v_mfma_f32_16x16x32_bf16 v[12:15], v[136:139], v[64:67], v[12:15]
	s_waitcnt lgkmcnt(0)
	v_mfma_f32_16x16x32_bf16 v[12:15], v[140:143], v[68:71], v[12:15]
	s_nop 7
	v_max3_f32 v203, v0, v1, v2
	v_max3_f32 v203, v203, v3, v4
	v_max3_f32 v203, v203, v5, v6
	v_max3_f32 v203, v203, v7, v8
	v_max3_f32 v203, v203, v9, v10
	v_max3_f32 v203, v203, v11, v12
	v_max3_f32 v203, v203, v13, v14
	v_max_f32_e32 v203, v203, v15
	v_mov_b32_e32 v205, v203
	s_nop 1
	v_permlane16_swap_b32_e32 v203, v205
	v_max_f32_e32 v203, v203, v205
	v_mov_b32_e32 v205, v203
	s_nop 1
	v_permlane32_swap_b32_e32 v203, v205
	v_max_f32_e32 v203, v203, v205
	v_max_f32_e32 v218, v200, v203
	v_sub_f32_e32 v220, v200, v218
	v_mov_b32_e32 v219, v218
	v_exp_f32_e32 v220, v220
	v_mov_b32_e32 v200, v218
	v_pk_add_f32 v[0:1], v[0:1], v[218:219] neg_lo:[0,1] neg_hi:[0,1]
	v_pk_add_f32 v[2:3], v[2:3], v[218:219] neg_lo:[0,1] neg_hi:[0,1]
	v_pk_add_f32 v[4:5], v[4:5], v[218:219] neg_lo:[0,1] neg_hi:[0,1]
	v_pk_add_f32 v[6:7], v[6:7], v[218:219] neg_lo:[0,1] neg_hi:[0,1]
	v_pk_add_f32 v[8:9], v[8:9], v[218:219] neg_lo:[0,1] neg_hi:[0,1]
	v_pk_add_f32 v[10:11], v[10:11], v[218:219] neg_lo:[0,1] neg_hi:[0,1]
	v_pk_add_f32 v[12:13], v[12:13], v[218:219] neg_lo:[0,1] neg_hi:[0,1]
	v_pk_add_f32 v[14:15], v[14:15], v[218:219] neg_lo:[0,1] neg_hi:[0,1]
	v_exp_f32_e32 v0, v0
	s_waitcnt vmcnt(0)
	v_exp_f32_e32 v1, v1
	ds_write_b128 v150, v[80:83] offset:0
	v_exp_f32_e32 v2, v2
	ds_write_b128 v150, v[84:87] offset:4096
	v_exp_f32_e32 v3, v3
	ds_write_b128 v150, v[88:91] offset:8192
	v_exp_f32_e32 v4, v4
	ds_write_b128 v150, v[92:95] offset:12288
	v_exp_f32_e32 v5, v5
	ds_write_b64 v151, v[96:97] offset:0
	v_exp_f32_e32 v6, v6
	ds_write_b64 v229, v[98:99] offset:0
	v_exp_f32_e32 v7, v7
	ds_write_b64 v151, v[100:101] offset:4096
	v_exp_f32_e32 v8, v8
	ds_write_b64 v229, v[102:103] offset:4096
	v_exp_f32_e32 v9, v9
	ds_write_b64 v151, v[104:105] offset:8192
	v_exp_f32_e32 v10, v10
	ds_write_b64 v229, v[106:107] offset:8192
	v_exp_f32_e32 v11, v11
	ds_write_b64 v151, v[108:109] offset:12288
	v_exp_f32_e32 v12, v12
	ds_write_b64 v229, v[110:111] offset:12288
	v_exp_f32_e32 v13, v13
	s_add_u32 s100, s16, 0xc0000
	v_exp_f32_e32 v14, v14
	s_addc_u32 s101, s17, 0
	v_exp_f32_e32 v15, v15
	s_add_u32 s0, s36, 0x100
	s_addc_u32 s1, s37, 0
	global_load_dwordx4 v[80:83], v154, s[100:101] offset:2048
	global_load_dwordx4 v[96:99], v162, s[0:1]
	global_load_dwordx4 v[84:87], v155, s[100:101] offset:2048
	global_load_dwordx4 v[100:103], v163, s[0:1]
	global_load_dwordx4 v[88:91], v156, s[100:101] offset:2048
	global_load_dwordx4 v[104:107], v164, s[0:1]
	global_load_dwordx4 v[92:95], v157, s[100:101] offset:2048
	global_load_dwordx4 v[108:111], v165, s[0:1]
	s_and_b32 s0, s3, 0xff
	s_add_u32 s0, s0, 1
	s_min_u32 s0, s0, 15
	s_lshr_b32 s1, s0, 2
	s_and_b32 s0, s0, 3
	s_lshl_b32 s0, s0, 5
	s_lshr_b32 vcc_lo, s3, 12
	s_add_u32 s0, s0, vcc_lo
	s_sub_i32 vcc_lo, s0, 4
	s_max_i32 vcc_lo, vcc_lo, 0
	s_min_i32 vcc_lo, vcc_lo, 0x78
	s_lshl_b32 vcc_hi, s1, 13
	s_lshl_b32 m0, vcc_lo, 6
	s_add_u32 m0, m0, vcc_hi
	s_mul_i32 m0, m0, 0x1800
	s_add_u32 s12, s4, m0
	s_addc_u32 s13, s5, 0
	s_lshl_b32 m0, s1, 24
	s_lshl_b32 s100, vcc_lo, 7
	s_add_u32 m0, m0, s100
	s_add_u32 s14, s6, m0
	s_addc_u32 s15, s7, 0
	s_lshl_b32 m0, s0, 6
	s_add_u32 m0, m0, vcc_hi
	s_mul_i32 m0, m0, 0x1800
	s_add_u32 s100, s4, m0
	s_addc_u32 s101, s5, 0
	global_load_dwordx4 v[72:75], v166, s[100:101]
	global_load_dwordx4 v[76:79], v166, s[100:101] offset:64
	ds_read_b128 v[112:115], v146 offset:32768
	ds_read_b128 v[116:119], v146 offset:36864
	ds_read_b128 v[120:123], v146 offset:40960
	ds_read_b128 v[124:127], v146 offset:45056
	ds_read_b128 v[128:131], v147 offset:32768
	ds_read_b128 v[132:135], v147 offset:36864
	ds_read_b128 v[136:139], v147 offset:40960
	ds_read_b128 v[140:143], v147 offset:45056
	v_mov_b32_e32 v221, v220
	v_pk_add_f32 v[222:223], v[0:1], v[2:3]
	v_pk_add_f32 v[222:223], v[222:223], v[4:5]
	v_pk_add_f32 v[222:223], v[222:223], v[6:7]
	v_pk_add_f32 v[222:223], v[222:223], v[8:9]
	v_pk_add_f32 v[222:223], v[222:223], v[10:11]
	v_pk_add_f32 v[222:223], v[222:223], v[12:13]
	v_pk_add_f32 v[222:223], v[222:223], v[14:15]
	v_pk_mul_f32 v[32:33], v[32:33], v[220:221]
	v_pk_mul_f32 v[34:35], v[34:35], v[220:221]
	v_pk_mul_f32 v[36:37], v[36:37], v[220:221]
	v_pk_mul_f32 v[38:39], v[38:39], v[220:221]
	v_pk_mul_f32 v[40:41], v[40:41], v[220:221]
	v_pk_mul_f32 v[42:43], v[42:43], v[220:221]
	v_pk_mul_f32 v[44:45], v[44:45], v[220:221]
	v_pk_mul_f32 v[46:47], v[46:47], v[220:221]
	v_add_f32_e32 v203, v222, v223
	v_fma_f32 v201, v201, v220, v203
	v_cvt_pk_bf16_f32 v48, v0, v1
	v_cvt_pk_bf16_f32 v49, v2, v3
	v_cvt_pk_bf16_f32 v50, v4, v5
	v_cvt_pk_bf16_f32 v51, v6, v7
	v_cvt_pk_bf16_f32 v52, v8, v9
	v_cvt_pk_bf16_f32 v53, v10, v11
	v_cvt_pk_bf16_f32 v54, v12, v13
	v_cvt_pk_bf16_f32 v55, v14, v15
	s_waitcnt lgkmcnt(7)
	v_mfma_f32_16x16x32_bf16 v[32:35], v[112:115], v[48:51], v[32:35]
	s_waitcnt lgkmcnt(6)
	v_mfma_f32_16x16x32_bf16 v[36:39], v[116:119], v[48:51], v[36:39]
	s_waitcnt lgkmcnt(5)
	v_mfma_f32_16x16x32_bf16 v[40:43], v[120:123], v[48:51], v[40:43]
	s_waitcnt lgkmcnt(4)
	v_mfma_f32_16x16x32_bf16 v[44:47], v[124:127], v[48:51], v[44:47]
	s_waitcnt lgkmcnt(3)
	v_mfma_f32_16x16x32_bf16 v[32:35], v[128:131], v[52:55], v[32:35]
	s_waitcnt lgkmcnt(2)
	v_mfma_f32_16x16x32_bf16 v[36:39], v[132:135], v[52:55], v[36:39]
	s_waitcnt lgkmcnt(1)
	v_mfma_f32_16x16x32_bf16 v[40:43], v[136:139], v[52:55], v[40:43]
	s_waitcnt lgkmcnt(0)
	v_mfma_f32_16x16x32_bf16 v[44:47], v[140:143], v[52:55], v[44:47]
	s_waitcnt lgkmcnt(0)
	s_barrier
; __device__ __forceinline__ void attn_phase(const Params& P, char* smem_raw) {
;     ...
;       for (int i = 0; i < 4; ++i) {
;         const int idx = tid + 256 * i;
;         *reinterpret_cast<uint4*>(&sm_k[(idx >> 3) * LDSS + (idx & 7) * 8]) = kreg[i];
;         *reinterpret_cast<uint4*>(&sm_vt[(idx >> 4) * 136 + (idx & 15) * 8]) = vreg[i];
;       }
;       __syncthreads();
;       f32x4 sacc[8];
; #pragma unroll
;       for (int t8 = 0; t8 < 8; ++t8) sacc[t8] = f32x4{0.f, 0.f, 0.f, 0.f};
; #pragma unroll
;       for (int s = 0; s < 2; ++s)
; #pragma unroll
;         for (int t8 = 0; t8 < 8; ++t8) {
;           const bf16x8 kf = *reinterpret_cast<const bf16x8*>(&sm_k[(t8 * 16 + (lane_c & 15)) * LDSS + s * 32 + (lane_c >> 4) * 8]);
;           sacc[t8] = __builtin_amdgcn_mfma_f32_16x16x32_bf16(qf[s], kf, sacc[t8], 0, 0, 0);
;         }
;       if (ck < 5) {
;         ATT_ISSUE(t, ck + 1)
;       } else if (t + VGRID < 8192) {
;         ATT_ISSUE(t + VGRID, 0)
;         ATT_QLOAD(t + VGRID)
;       }
;       if (ck < 4) {
;         const float* rb0 = sm_rpb + (rs + ck * 2 - r + 7) * 31;
; #pragma unroll
;         for (int t8 = 0; t8 < 8; ++t8)
; #pragma unroll
;           for (int reg = 0; reg < 4; ++reg)
;             sacc[t8][reg] += rb0[(t8 >> 2) * 31 + dco[reg][t8 & 3]];
;       }
; #pragma unroll
;       for (int reg = 0; reg < 4; ++reg) {
;         float mx = sacc[0][reg];
; #pragma unroll
;         for (int t8 = 1; t8 < 8; ++t8) mx = fmaxf(mx, sacc[t8][reg]);
;         mx = row16_max(mx);
;         const float mnew = fmaxf(mrow[reg], mx);
;         const float alpha = __builtin_amdgcn_exp2f(mrow[reg] - mnew);
;         mrow[reg] = mnew;
;         float rsum = 0.f;
; #pragma unroll
;         for (int t8 = 0; t8 < 8; ++t8) {
;           const float p = __builtin_amdgcn_exp2f(sacc[t8][reg] - mnew);
;           rsum += p;
;           sm_p[(wid * 16 + (lane_c >> 4) * 4 + reg) * 136 + t8 * 16 + (lane_c & 15)] = f2bf(p);
;         }
;         rsum = row16_sum(rsum);
;         lrow[reg] = lrow[reg] * alpha + rsum;
; #pragma unroll
;         for (int td = 0; td < 4; ++td) o[td][reg] *= alpha;
;       }
	ds_read_b128 v[112:115], v149 offset:0
	ds_read_b128 v[116:119], v224 offset:0
	ds_read_b128 v[120:123], v149 offset:8192
	ds_read_b128 v[124:127], v224 offset:8192
	ds_read_b128 v[128:131], v149 offset:2048
	ds_read_b128 v[132:135], v224 offset:2048
	ds_read_b128 v[136:139], v149 offset:10240
	ds_read_b128 v[140:143], v224 offset:10240
	s_waitcnt lgkmcnt(7)
	v_mfma_f32_16x16x32_bf16 v[0:3], v[112:115], v[64:67], 0
	ds_read_b128 v[112:115], v149 offset:4096
	s_waitcnt lgkmcnt(7)
	v_mfma_f32_16x16x32_bf16 v[0:3], v[116:119], v[68:71], v[0:3]
	ds_read_b128 v[116:119], v224 offset:4096
	s_waitcnt lgkmcnt(7)
	v_mfma_f32_16x16x32_bf16 v[4:7], v[120:123], v[64:67], 0
	ds_read_b128 v[120:123], v149 offset:12288
	s_waitcnt lgkmcnt(7)
	v_mfma_f32_16x16x32_bf16 v[4:7], v[124:127], v[68:71], v[4:7]
	ds_read_b128 v[124:127], v224 offset:12288
	s_waitcnt lgkmcnt(7)
	v_mfma_f32_16x16x32_bf16 v[8:11], v[128:131], v[64:67], 0
	ds_read_b128 v[128:131], v149 offset:6144
	s_waitcnt lgkmcnt(7)
	v_mfma_f32_16x16x32_bf16 v[8:11], v[132:135], v[68:71], v[8:11]
	ds_read_b128 v[132:135], v224 offset:6144
	s_waitcnt lgkmcnt(7)
	v_mfma_f32_16x16x32_bf16 v[12:15], v[136:139], v[64:67], 0
	ds_read_b128 v[136:139], v149 offset:14336
	s_waitcnt lgkmcnt(7)
	v_mfma_f32_16x16x32_bf16 v[12:15], v[140:143], v[68:71], v[12:15]
	ds_read_b128 v[140:143], v224 offset:14336
	s_waitcnt lgkmcnt(7)
	v_mfma_f32_16x16x32_bf16 v[16:19], v[112:115], v[64:67], 0
	s_waitcnt lgkmcnt(6)
	v_mfma_f32_16x16x32_bf16 v[16:19], v[116:119], v[68:71], v[16:19]
	s_waitcnt lgkmcnt(5)
	v_mfma_f32_16x16x32_bf16 v[20:23], v[120:123], v[64:67], 0
	s_waitcnt lgkmcnt(4)
	v_mfma_f32_16x16x32_bf16 v[20:23], v[124:127], v[68:71], v[20:23]
	s_waitcnt lgkmcnt(3)
	v_mfma_f32_16x16x32_bf16 v[24:27], v[128:131], v[64:67], 0
	s_waitcnt lgkmcnt(2)
	v_mfma_f32_16x16x32_bf16 v[24:27], v[132:135], v[68:71], v[24:27]
	s_waitcnt lgkmcnt(1)
	v_mfma_f32_16x16x32_bf16 v[28:31], v[136:139], v[64:67], 0
	s_waitcnt lgkmcnt(0)
	v_mfma_f32_16x16x32_bf16 v[28:31], v[140:143], v[68:71], v[28:31]
	s_nop 7
	v_max3_f32 v203, v0, v1, v2
	v_max3_f32 v203, v203, v3, v4
	v_max3_f32 v203, v203, v5, v6
	v_max3_f32 v203, v203, v7, v8
	v_max3_f32 v203, v203, v9, v10
	v_max3_f32 v203, v203, v11, v12
	v_max3_f32 v203, v203, v13, v14
	v_max3_f32 v203, v203, v15, v16
	v_max3_f32 v203, v203, v17, v18
	v_max3_f32 v203, v203, v19, v20
	v_max3_f32 v203, v203, v21, v22
	v_max3_f32 v203, v203, v23, v24
	v_max3_f32 v203, v203, v25, v26
	v_max3_f32 v203, v203, v27, v28
	v_max3_f32 v203, v203, v29, v30
	v_max_f32_e32 v203, v203, v31
	v_mov_b32_e32 v205, v203
	s_nop 1
	v_permlane16_swap_b32_e32 v203, v205
	v_max_f32_e32 v203, v203, v205
	v_mov_b32_e32 v205, v203
	s_nop 1
	v_permlane32_swap_b32_e32 v203, v205
	v_max_f32_e32 v203, v203, v205
	v_max_f32_e32 v218, v200, v203
	v_sub_f32_e32 v220, v200, v218
	v_mov_b32_e32 v219, v218
	v_exp_f32_e32 v220, v220
	v_mov_b32_e32 v200, v218
	v_pk_add_f32 v[0:1], v[0:1], v[218:219] neg_lo:[0,1] neg_hi:[0,1]
	v_pk_add_f32 v[2:3], v[2:3], v[218:219] neg_lo:[0,1] neg_hi:[0,1]
	v_pk_add_f32 v[4:5], v[4:5], v[218:219] neg_lo:[0,1] neg_hi:[0,1]
	v_pk_add_f32 v[6:7], v[6:7], v[218:219] neg_lo:[0,1] neg_hi:[0,1]
	v_pk_add_f32 v[8:9], v[8:9], v[218:219] neg_lo:[0,1] neg_hi:[0,1]
	v_pk_add_f32 v[10:11], v[10:11], v[218:219] neg_lo:[0,1] neg_hi:[0,1]
	v_pk_add_f32 v[12:13], v[12:13], v[218:219] neg_lo:[0,1] neg_hi:[0,1]
	v_pk_add_f32 v[14:15], v[14:15], v[218:219] neg_lo:[0,1] neg_hi:[0,1]
	v_pk_add_f32 v[16:17], v[16:17], v[218:219] neg_lo:[0,1] neg_hi:[0,1]
	v_pk_add_f32 v[18:19], v[18:19], v[218:219] neg_lo:[0,1] neg_hi:[0,1]
	v_pk_add_f32 v[20:21], v[20:21], v[218:219] neg_lo:[0,1] neg_hi:[0,1]
	v_pk_add_f32 v[22:23], v[22:23], v[218:219] neg_lo:[0,1] neg_hi:[0,1]
	v_pk_add_f32 v[24:25], v[24:25], v[218:219] neg_lo:[0,1] neg_hi:[0,1]
	v_pk_add_f32 v[26:27], v[26:27], v[218:219] neg_lo:[0,1] neg_hi:[0,1]
	v_pk_add_f32 v[28:29], v[28:29], v[218:219] neg_lo:[0,1] neg_hi:[0,1]
	v_pk_add_f32 v[30:31], v[30:31], v[218:219] neg_lo:[0,1] neg_hi:[0,1]
	v_exp_f32_e32 v0, v0
	s_waitcnt vmcnt(2)
	v_exp_f32_e32 v1, v1
	ds_write_b128 v150, v[80:83] offset:32768
	v_exp_f32_e32 v2, v2
	ds_write_b128 v150, v[84:87] offset:36864
	v_exp_f32_e32 v3, v3
	ds_write_b128 v150, v[88:91] offset:40960
	v_exp_f32_e32 v4, v4
	ds_write_b128 v150, v[92:95] offset:45056
	v_exp_f32_e32 v5, v5
	ds_write_b64 v151, v[96:97] offset:32768
	v_exp_f32_e32 v6, v6
	ds_write_b64 v229, v[98:99] offset:32768
	v_exp_f32_e32 v7, v7
	ds_write_b64 v151, v[100:101] offset:36864
	v_exp_f32_e32 v8, v8
	ds_write_b64 v229, v[102:103] offset:36864
	v_exp_f32_e32 v9, v9
	ds_write_b64 v151, v[104:105] offset:40960
	v_exp_f32_e32 v10, v10
	ds_write_b64 v229, v[106:107] offset:40960
	v_exp_f32_e32 v11, v11
	ds_write_b64 v151, v[108:109] offset:45056
	v_exp_f32_e32 v12, v12
	ds_write_b64 v229, v[110:111] offset:45056
	v_exp_f32_e32 v13, v13
	s_add_u32 s100, s12, 0x0
	v_exp_f32_e32 v14, v14
	s_addc_u32 s101, s13, 0
	v_exp_f32_e32 v15, v15
	s_add_u32 s0, s14, 0x0
	v_exp_f32_e32 v16, v16
	s_addc_u32 s1, s15, 0
	v_exp_f32_e32 v17, v17
	global_load_dwordx4 v[80:83], v154, s[100:101] offset:2048
	v_exp_f32_e32 v18, v18
	global_load_dwordx4 v[96:99], v158, s[0:1]
	v_exp_f32_e32 v19, v19
	global_load_dwordx4 v[84:87], v155, s[100:101] offset:2048
	v_exp_f32_e32 v20, v20
	global_load_dwordx4 v[100:103], v159, s[0:1]
	v_exp_f32_e32 v21, v21
	global_load_dwordx4 v[88:91], v156, s[100:101] offset:2048
	v_exp_f32_e32 v22, v22
	global_load_dwordx4 v[104:107], v160, s[0:1]
	v_exp_f32_e32 v23, v23
	global_load_dwordx4 v[92:95], v157, s[100:101] offset:2048
	v_exp_f32_e32 v24, v24
; __device__ __forceinline__ void attn_phase(const Params& P, char* smem_raw) {
;     ...
;       if (ck < 4) {
;         const float* rb0 = sm_rpb + (rs + ck * 2 - r + 7) * 31;
; #pragma unroll
;         for (int t8 = 0; t8 < 8; ++t8)
; #pragma unroll
;           for (int reg = 0; reg < 4; ++reg)
;             sacc[t8][reg] += rb0[(t8 >> 2) * 31 + dco[reg][t8 & 3]];
;       }
; #pragma unroll
;       for (int reg = 0; reg < 4; ++reg) {
;         float mx = sacc[0][reg];
; #pragma unroll
;         for (int t8 = 1; t8 < 8; ++t8) mx = fmaxf(mx, sacc[t8][reg]);
;         mx = row16_max(mx);
;         const float mnew = fmaxf(mrow[reg], mx);
;         const float alpha = __builtin_amdgcn_exp2f(mrow[reg] - mnew);
;         mrow[reg] = mnew;
;         float rsum = 0.f;
; #pragma unroll
;         for (int t8 = 0; t8 < 8; ++t8) {
;           const float p = __builtin_amdgcn_exp2f(sacc[t8][reg] - mnew);
;           rsum += p;
;           sm_p[(wid * 16 + (lane_c >> 4) * 4 + reg) * 136 + t8 * 16 + (lane_c & 15)] = f2bf(p);
;         }
;         rsum = row16_sum(rsum);
;         lrow[reg] = lrow[reg] * alpha + rsum;
; #pragma unroll
;         for (int td = 0; td < 4; ++td) o[td][reg] *= alpha;
;       }
;       asm volatile("s_waitcnt lgkmcnt(0)" ::: "memory");
; #pragma unroll
;       for (int s4 = 0; s4 < 4; ++s4) {
;         const bf16x8 pf = *reinterpret_cast<const bf16x8*>(&sm_p[(wid * 16 + (lane_c & 15)) * 136 + s4 * 32 + (lane_c >> 4) * 8]);
; #pragma unroll
;         for (int td = 0; td < 4; ++td) {
;           const bf16x8 vf = *reinterpret_cast<const bf16x8*>(&sm_vt[(td * 16 + (lane_c & 15)) * 136 + s4 * 32 + (lane_c >> 4) * 8]);
;           o[td] = __builtin_amdgcn_mfma_f32_16x16x32_bf16(pf, vf, o[td], 0, 0, 0);
;         }
;       }
	global_load_dwordx4 v[108:111], v161, s[0:1]
	v_exp_f32_e32 v25, v25
	v_exp_f32_e32 v26, v26
	v_exp_f32_e32 v27, v27
	v_exp_f32_e32 v28, v28
	v_exp_f32_e32 v29, v29
	v_exp_f32_e32 v30, v30
	v_exp_f32_e32 v31, v31
	s_and_b32 s0, s3, 0xff
	s_add_u32 s0, s0, 1
	s_min_u32 s0, s0, 15
	s_lshr_b32 s1, s0, 2
	s_and_b32 s0, s0, 3
	s_lshl_b32 s0, s0, 5
	s_lshr_b32 vcc_lo, s3, 12
	s_add_u32 s0, s0, vcc_lo
	s_sub_i32 vcc_lo, s0, 4
	s_max_i32 vcc_lo, vcc_lo, 0
	s_min_i32 vcc_lo, vcc_lo, 0x78
	s_lshl_b32 vcc_hi, s1, 13
	s_sub_i32 vcc_lo, vcc_lo, s0
	s_add_i32 vcc_lo, vcc_lo, 4
	s_lshl_b32 vcc_lo, vcc_lo, 7
	s_bfe_u32 m0, s3, 0x10008
	s_mul_i32 m0, m0, 0x12000
	s_add_i32 vcc_lo, vcc_lo, m0
	s_add_i32 vcc_lo, vcc_lo, 0x10010
	v_add_u32_e32 v184, vcc_lo, v168
	v_add_u32_e32 v185, vcc_lo, v169
	v_add_u32_e32 v186, vcc_lo, v170
	v_add_u32_e32 v187, vcc_lo, v171
	v_add_u32_e32 v188, vcc_lo, v172
	v_add_u32_e32 v189, vcc_lo, v173
	v_add_u32_e32 v190, vcc_lo, v174
	v_add_u32_e32 v191, vcc_lo, v175
	ds_read_b128 v[112:115], v225 offset:0
	ds_read_b128 v[116:119], v225 offset:4096
	ds_read_b128 v[120:123], v225 offset:8192
	ds_read_b128 v[124:127], v225 offset:12288
	ds_read_b128 v[128:131], v226 offset:0
	ds_read_b128 v[132:135], v226 offset:4096
	ds_read_b128 v[136:139], v226 offset:8192
	ds_read_b128 v[140:143], v226 offset:12288
	v_mov_b32_e32 v221, v220
	v_pk_add_f32 v[222:223], v[0:1], v[2:3]
	v_pk_add_f32 v[222:223], v[222:223], v[4:5]
	v_pk_add_f32 v[222:223], v[222:223], v[6:7]
	v_pk_add_f32 v[222:223], v[222:223], v[8:9]
	v_pk_add_f32 v[222:223], v[222:223], v[10:11]
	v_pk_add_f32 v[222:223], v[222:223], v[12:13]
	v_pk_add_f32 v[222:223], v[222:223], v[14:15]
	v_pk_add_f32 v[222:223], v[222:223], v[16:17]
	v_pk_add_f32 v[222:223], v[222:223], v[18:19]
	v_pk_add_f32 v[222:223], v[222:223], v[20:21]
	v_pk_add_f32 v[222:223], v[222:223], v[22:23]
	v_pk_add_f32 v[222:223], v[222:223], v[24:25]
	v_pk_add_f32 v[222:223], v[222:223], v[26:27]
	v_pk_add_f32 v[222:223], v[222:223], v[28:29]
	v_pk_add_f32 v[222:223], v[222:223], v[30:31]
	v_pk_mul_f32 v[32:33], v[32:33], v[220:221]
	v_pk_mul_f32 v[34:35], v[34:35], v[220:221]
	v_pk_mul_f32 v[36:37], v[36:37], v[220:221]
	v_pk_mul_f32 v[38:39], v[38:39], v[220:221]
	v_pk_mul_f32 v[40:41], v[40:41], v[220:221]
	v_pk_mul_f32 v[42:43], v[42:43], v[220:221]
	v_pk_mul_f32 v[44:45], v[44:45], v[220:221]
	v_pk_mul_f32 v[46:47], v[46:47], v[220:221]
	v_add_f32_e32 v203, v222, v223
	v_fma_f32 v201, v201, v220, v203
	v_cvt_pk_bf16_f32 v48, v0, v1
	v_cvt_pk_bf16_f32 v49, v2, v3
	v_cvt_pk_bf16_f32 v50, v4, v5
	v_cvt_pk_bf16_f32 v51, v6, v7
	v_cvt_pk_bf16_f32 v52, v8, v9
	v_cvt_pk_bf16_f32 v53, v10, v11
	v_cvt_pk_bf16_f32 v54, v12, v13
	v_cvt_pk_bf16_f32 v55, v14, v15
	v_cvt_pk_bf16_f32 v56, v16, v17
	v_cvt_pk_bf16_f32 v57, v18, v19
	v_cvt_pk_bf16_f32 v58, v20, v21
	v_cvt_pk_bf16_f32 v59, v22, v23
	v_cvt_pk_bf16_f32 v60, v24, v25
	v_cvt_pk_bf16_f32 v61, v26, v27
	v_cvt_pk_bf16_f32 v62, v28, v29
	v_cvt_pk_bf16_f32 v63, v30, v31
	s_waitcnt lgkmcnt(7)
	v_mfma_f32_16x16x32_bf16 v[32:35], v[112:115], v[48:51], v[32:35]
	ds_read_b128 v[112:115], v227 offset:0
	s_waitcnt lgkmcnt(7)
	v_mfma_f32_16x16x32_bf16 v[36:39], v[116:119], v[48:51], v[36:39]
	ds_read_b128 v[116:119], v227 offset:4096
	s_waitcnt lgkmcnt(7)
	v_mfma_f32_16x16x32_bf16 v[40:43], v[120:123], v[48:51], v[40:43]
	ds_read_b128 v[120:123], v227 offset:8192
	s_waitcnt lgkmcnt(7)
	v_mfma_f32_16x16x32_bf16 v[44:47], v[124:127], v[48:51], v[44:47]
	ds_read_b128 v[124:127], v227 offset:12288
	s_waitcnt lgkmcnt(7)
	v_mfma_f32_16x16x32_bf16 v[32:35], v[128:131], v[52:55], v[32:35]
	ds_read_b128 v[128:131], v228 offset:0
	s_waitcnt lgkmcnt(7)
	v_mfma_f32_16x16x32_bf16 v[36:39], v[132:135], v[52:55], v[36:39]
	ds_read_b128 v[132:135], v228 offset:4096
	s_waitcnt lgkmcnt(7)
	v_mfma_f32_16x16x32_bf16 v[40:43], v[136:139], v[52:55], v[40:43]
	ds_read_b128 v[136:139], v228 offset:8192
	s_waitcnt lgkmcnt(7)
	v_mfma_f32_16x16x32_bf16 v[44:47], v[140:143], v[52:55], v[44:47]
	ds_read_b128 v[140:143], v228 offset:12288
	s_waitcnt lgkmcnt(7)
	v_mfma_f32_16x16x32_bf16 v[32:35], v[112:115], v[56:59], v[32:35]
	s_waitcnt lgkmcnt(6)
	v_mfma_f32_16x16x32_bf16 v[36:39], v[116:119], v[56:59], v[36:39]
	s_waitcnt lgkmcnt(5)
	v_mfma_f32_16x16x32_bf16 v[40:43], v[120:123], v[56:59], v[40:43]
	s_waitcnt lgkmcnt(4)
	v_mfma_f32_16x16x32_bf16 v[44:47], v[124:127], v[56:59], v[44:47]
	s_waitcnt lgkmcnt(3)
	v_mfma_f32_16x16x32_bf16 v[32:35], v[128:131], v[60:63], v[32:35]
	s_waitcnt lgkmcnt(2)
	v_mfma_f32_16x16x32_bf16 v[36:39], v[132:135], v[60:63], v[36:39]
	s_waitcnt lgkmcnt(1)
	v_mfma_f32_16x16x32_bf16 v[40:43], v[136:139], v[60:63], v[40:43]
	s_waitcnt lgkmcnt(0)
	v_mfma_f32_16x16x32_bf16 v[44:47], v[140:143], v[60:63], v[44:47]
	s_waitcnt lgkmcnt(0)
	s_barrier
; __device__ __forceinline__ void attn_phase(const Params& P, char* smem_raw) {
;     ...
;       for (int i = 0; i < 4; ++i) {
;         const int idx = tid + 256 * i;
;         *reinterpret_cast<uint4*>(&sm_k[(idx >> 3) * LDSS + (idx & 7) * 8]) = kreg[i];
;         *reinterpret_cast<uint4*>(&sm_vt[(idx >> 4) * 136 + (idx & 15) * 8]) = vreg[i];
;       }
;       __syncthreads();
;       f32x4 sacc[8];
; #pragma unroll
;       for (int t8 = 0; t8 < 8; ++t8) sacc[t8] = f32x4{0.f, 0.f, 0.f, 0.f};
; #pragma unroll
;       for (int s = 0; s < 2; ++s)
; #pragma unroll
;         for (int t8 = 0; t8 < 8; ++t8) {
;           const bf16x8 kf = *reinterpret_cast<const bf16x8*>(&sm_k[(t8 * 16 + (lane_c & 15)) * LDSS + s * 32 + (lane_c >> 4) * 8]);
;           sacc[t8] = __builtin_amdgcn_mfma_f32_16x16x32_bf16(qf[s], kf, sacc[t8], 0, 0, 0);
;         }
;       if (ck < 5) {
;         ATT_ISSUE(t, ck + 1)
;       } else if (t + VGRID < 8192) {
;         ATT_ISSUE(t + VGRID, 0)
;         ATT_QLOAD(t + VGRID)
;       }
;       if (ck < 4) {
;         const float* rb0 = sm_rpb + (rs + ck * 2 - r + 7) * 31;
; #pragma unroll
;         for (int t8 = 0; t8 < 8; ++t8)
; #pragma unroll
;           for (int reg = 0; reg < 4; ++reg)
;             sacc[t8][reg] += rb0[(t8 >> 2) * 31 + dco[reg][t8 & 3]];
;       }
; #pragma unroll
;       for (int reg = 0; reg < 4; ++reg) {
;         float mx = sacc[0][reg];
; #pragma unroll
;         for (int t8 = 1; t8 < 8; ++t8) mx = fmaxf(mx, sacc[t8][reg]);
;         mx = row16_max(mx);
;         const float mnew = fmaxf(mrow[reg], mx);
;         const float alpha = __builtin_amdgcn_exp2f(mrow[reg] - mnew);
;         mrow[reg] = mnew;
;         float rsum = 0.f;
; #pragma unroll
;         for (int t8 = 0; t8 < 8; ++t8) {
;           const float p = __builtin_amdgcn_exp2f(sacc[t8][reg] - mnew);
;           rsum += p;
;           sm_p[(wid * 16 + (lane_c >> 4) * 4 + reg) * 136 + t8 * 16 + (lane_c & 15)] = f2bf(p);
;         }
;         rsum = row16_sum(rsum);
;         lrow[reg] = lrow[reg] * alpha + rsum;
; #pragma unroll
;         for (int td = 0; td < 4; ++td) o[td][reg] *= alpha;
;       }
	ds_read_b128 v[112:115], v149 offset:32768
	ds_read_b128 v[116:119], v224 offset:32768
	ds_read_b128 v[120:123], v149 offset:40960
	ds_read_b128 v[124:127], v224 offset:40960
	ds_read_b128 v[128:131], v149 offset:34816
	ds_read_b128 v[132:135], v224 offset:34816
	ds_read_b128 v[136:139], v149 offset:43008
	ds_read_b128 v[140:143], v224 offset:43008
	s_waitcnt lgkmcnt(7)
	v_mfma_f32_16x16x32_bf16 v[0:3], v[112:115], v[64:67], 0
	ds_read_b128 v[112:115], v149 offset:36864
	s_waitcnt lgkmcnt(7)
	v_mfma_f32_16x16x32_bf16 v[0:3], v[116:119], v[68:71], v[0:3]
	ds_read_b128 v[116:119], v224 offset:36864
	s_waitcnt lgkmcnt(7)
	v_mfma_f32_16x16x32_bf16 v[4:7], v[120:123], v[64:67], 0
	ds_read_b128 v[120:123], v149 offset:45056
	s_waitcnt lgkmcnt(7)
	v_mfma_f32_16x16x32_bf16 v[4:7], v[124:127], v[68:71], v[4:7]
	ds_read_b128 v[124:127], v224 offset:45056
	s_waitcnt lgkmcnt(7)
	v_mfma_f32_16x16x32_bf16 v[8:11], v[128:131], v[64:67], 0
	ds_read_b128 v[128:131], v149 offset:38912
	s_waitcnt lgkmcnt(7)
	v_mfma_f32_16x16x32_bf16 v[8:11], v[132:135], v[68:71], v[8:11]
	ds_read_b128 v[132:135], v224 offset:38912
	s_waitcnt lgkmcnt(7)
	v_mfma_f32_16x16x32_bf16 v[12:15], v[136:139], v[64:67], 0
	ds_read_b128 v[136:139], v149 offset:47104
	s_waitcnt lgkmcnt(7)
	v_mfma_f32_16x16x32_bf16 v[12:15], v[140:143], v[68:71], v[12:15]
	ds_read_b128 v[140:143], v224 offset:47104
	s_waitcnt lgkmcnt(7)
	v_mfma_f32_16x16x32_bf16 v[16:19], v[112:115], v[64:67], 0
	s_waitcnt lgkmcnt(6)
	v_mfma_f32_16x16x32_bf16 v[16:19], v[116:119], v[68:71], v[16:19]
	s_waitcnt lgkmcnt(5)
	v_mfma_f32_16x16x32_bf16 v[20:23], v[120:123], v[64:67], 0
	s_waitcnt lgkmcnt(4)
	v_mfma_f32_16x16x32_bf16 v[20:23], v[124:127], v[68:71], v[20:23]
	s_waitcnt lgkmcnt(3)
	v_mfma_f32_16x16x32_bf16 v[24:27], v[128:131], v[64:67], 0
	s_waitcnt lgkmcnt(2)
	v_mfma_f32_16x16x32_bf16 v[24:27], v[132:135], v[68:71], v[24:27]
	s_waitcnt lgkmcnt(1)
	v_mfma_f32_16x16x32_bf16 v[28:31], v[136:139], v[64:67], 0
	s_waitcnt lgkmcnt(0)
	v_mfma_f32_16x16x32_bf16 v[28:31], v[140:143], v[68:71], v[28:31]
	s_nop 7
	v_max3_f32 v203, v0, v1, v2
	v_max3_f32 v203, v203, v3, v4
	v_max3_f32 v203, v203, v5, v6
	v_max3_f32 v203, v203, v7, v8
	v_max3_f32 v203, v203, v9, v10
	v_max3_f32 v203, v203, v11, v12
	v_max3_f32 v203, v203, v13, v14
	v_max3_f32 v203, v203, v15, v16
	v_max3_f32 v203, v203, v17, v18
	v_max3_f32 v203, v203, v19, v20
	v_max3_f32 v203, v203, v21, v22
	v_max3_f32 v203, v203, v23, v24
	v_max3_f32 v203, v203, v25, v26
	v_max3_f32 v203, v203, v27, v28
	v_max3_f32 v203, v203, v29, v30
	v_max_f32_e32 v203, v203, v31
	v_mov_b32_e32 v205, v203
	s_nop 1
	v_permlane16_swap_b32_e32 v203, v205
	v_max_f32_e32 v203, v203, v205
	v_mov_b32_e32 v205, v203
	s_nop 1
	v_permlane32_swap_b32_e32 v203, v205
	v_max_f32_e32 v203, v203, v205
	v_max_f32_e32 v218, v200, v203
	v_sub_f32_e32 v220, v200, v218
	v_mov_b32_e32 v219, v218
	v_exp_f32_e32 v220, v220
	v_mov_b32_e32 v200, v218
	v_pk_add_f32 v[0:1], v[0:1], v[218:219] neg_lo:[0,1] neg_hi:[0,1]
	v_pk_add_f32 v[2:3], v[2:3], v[218:219] neg_lo:[0,1] neg_hi:[0,1]
	v_pk_add_f32 v[4:5], v[4:5], v[218:219] neg_lo:[0,1] neg_hi:[0,1]
	v_pk_add_f32 v[6:7], v[6:7], v[218:219] neg_lo:[0,1] neg_hi:[0,1]
	v_pk_add_f32 v[8:9], v[8:9], v[218:219] neg_lo:[0,1] neg_hi:[0,1]
	v_pk_add_f32 v[10:11], v[10:11], v[218:219] neg_lo:[0,1] neg_hi:[0,1]
	v_pk_add_f32 v[12:13], v[12:13], v[218:219] neg_lo:[0,1] neg_hi:[0,1]
	v_pk_add_f32 v[14:15], v[14:15], v[218:219] neg_lo:[0,1] neg_hi:[0,1]
	v_pk_add_f32 v[16:17], v[16:17], v[218:219] neg_lo:[0,1] neg_hi:[0,1]
	v_pk_add_f32 v[18:19], v[18:19], v[218:219] neg_lo:[0,1] neg_hi:[0,1]
	v_pk_add_f32 v[20:21], v[20:21], v[218:219] neg_lo:[0,1] neg_hi:[0,1]
	v_pk_add_f32 v[22:23], v[22:23], v[218:219] neg_lo:[0,1] neg_hi:[0,1]
	v_pk_add_f32 v[24:25], v[24:25], v[218:219] neg_lo:[0,1] neg_hi:[0,1]
	v_pk_add_f32 v[26:27], v[26:27], v[218:219] neg_lo:[0,1] neg_hi:[0,1]
	v_pk_add_f32 v[28:29], v[28:29], v[218:219] neg_lo:[0,1] neg_hi:[0,1]
	v_pk_add_f32 v[30:31], v[30:31], v[218:219] neg_lo:[0,1] neg_hi:[0,1]
	v_exp_f32_e32 v0, v0
	s_waitcnt vmcnt(0)
	v_exp_f32_e32 v1, v1
	ds_write_b128 v150, v[80:83] offset:0
	v_exp_f32_e32 v2, v2
	ds_write_b128 v150, v[84:87] offset:4096
	v_exp_f32_e32 v3, v3
	ds_write_b128 v150, v[88:91] offset:8192
	v_exp_f32_e32 v4, v4
	ds_write_b128 v150, v[92:95] offset:12288
	v_exp_f32_e32 v5, v5
	ds_write_b64 v151, v[96:97] offset:0
	v_exp_f32_e32 v6, v6
	ds_write_b64 v229, v[98:99] offset:0
	v_exp_f32_e32 v7, v7
	ds_write_b64 v151, v[100:101] offset:4096
	v_exp_f32_e32 v8, v8
	ds_write_b64 v229, v[102:103] offset:4096
	v_exp_f32_e32 v9, v9
	ds_write_b64 v151, v[104:105] offset:8192
	v_exp_f32_e32 v10, v10
	ds_write_b64 v229, v[106:107] offset:8192
	v_exp_f32_e32 v11, v11
	ds_write_b64 v151, v[108:109] offset:12288
	v_exp_f32_e32 v12, v12
	ds_write_b64 v229, v[110:111] offset:12288
	v_exp_f32_e32 v13, v13
	s_add_u32 s100, s12, 0xc0000
	v_exp_f32_e32 v14, v14
	s_addc_u32 s101, s13, 0
	v_exp_f32_e32 v15, v15
	s_add_u32 s0, s14, 0x100
	v_exp_f32_e32 v16, v16
	s_addc_u32 s1, s15, 0
	v_exp_f32_e32 v17, v17
	global_load_dwordx4 v[80:83], v154, s[100:101] offset:2048
	v_exp_f32_e32 v18, v18
	global_load_dwordx4 v[96:99], v158, s[0:1]
	v_exp_f32_e32 v19, v19
	global_load_dwordx4 v[84:87], v155, s[100:101] offset:2048
	v_exp_f32_e32 v20, v20
	global_load_dwordx4 v[100:103], v159, s[0:1]
	v_exp_f32_e32 v21, v21
	global_load_dwordx4 v[88:91], v156, s[100:101] offset:2048
	v_exp_f32_e32 v22, v22
	global_load_dwordx4 v[104:107], v160, s[0:1]
	v_exp_f32_e32 v23, v23
	global_load_dwordx4 v[92:95], v157, s[100:101] offset:2048
	v_exp_f32_e32 v24, v24
; __device__ __forceinline__ void attn_phase(const Params& P, char* smem_raw) {
;     ...
; #pragma unroll
;       for (int s4 = 0; s4 < 4; ++s4) {
;         const bf16x8 pf = *reinterpret_cast<const bf16x8*>(&sm_p[(wid * 16 + (lane_c & 15)) * 136 + s4 * 32 + (lane_c >> 4) * 8]);
; #pragma unroll
;         for (int td = 0; td < 4; ++td) {
;           const bf16x8 vf = *reinterpret_cast<const bf16x8*>(&sm_vt[(td * 16 + (lane_c & 15)) * 136 + s4 * 32 + (lane_c >> 4) * 8]);
;           o[td] = __builtin_amdgcn_mfma_f32_16x16x32_bf16(pf, vf, o[td], 0, 0, 0);
;         }
;       }
;     }
;     u16* Ob = P.cat + ((long)b * 8192 + r * 64) * 1024 + h * 64;
; #pragma unroll
;     for (int td = 0; td < 4; ++td)
; #pragma unroll
;       for (int reg = 0; reg < 4; ++reg) {
;         const int rowl = wid * 16 + (lane >> 4) * 4 + reg;
;         Ob[(unsigned)(rowl * 1024 + td * 16 + (lane & 15))] = f2bf(o[td][reg] * __builtin_amdgcn_rcpf(lrow[reg]));
;       }
	global_load_dwordx4 v[108:111], v161, s[0:1]
	v_exp_f32_e32 v25, v25
	v_exp_f32_e32 v26, v26
	v_exp_f32_e32 v27, v27
	v_exp_f32_e32 v28, v28
	v_exp_f32_e32 v29, v29
	v_exp_f32_e32 v30, v30
	v_exp_f32_e32 v31, v31
	ds_read_b128 v[112:115], v225 offset:32768
	ds_read_b128 v[116:119], v225 offset:36864
	ds_read_b128 v[120:123], v225 offset:40960
	ds_read_b128 v[124:127], v225 offset:45056
	ds_read_b128 v[128:131], v226 offset:32768
	ds_read_b128 v[132:135], v226 offset:36864
	ds_read_b128 v[136:139], v226 offset:40960
	ds_read_b128 v[140:143], v226 offset:45056
	v_mov_b32_e32 v221, v220
	v_pk_add_f32 v[222:223], v[0:1], v[2:3]
	v_pk_add_f32 v[222:223], v[222:223], v[4:5]
	v_pk_add_f32 v[222:223], v[222:223], v[6:7]
	v_pk_add_f32 v[222:223], v[222:223], v[8:9]
	v_pk_add_f32 v[222:223], v[222:223], v[10:11]
	v_pk_add_f32 v[222:223], v[222:223], v[12:13]
	v_pk_add_f32 v[222:223], v[222:223], v[14:15]
	v_pk_add_f32 v[222:223], v[222:223], v[16:17]
	v_pk_add_f32 v[222:223], v[222:223], v[18:19]
	v_pk_add_f32 v[222:223], v[222:223], v[20:21]
	v_pk_add_f32 v[222:223], v[222:223], v[22:23]
	v_pk_add_f32 v[222:223], v[222:223], v[24:25]
	v_pk_add_f32 v[222:223], v[222:223], v[26:27]
	v_pk_add_f32 v[222:223], v[222:223], v[28:29]
	v_pk_add_f32 v[222:223], v[222:223], v[30:31]
	v_pk_mul_f32 v[32:33], v[32:33], v[220:221]
	v_pk_mul_f32 v[34:35], v[34:35], v[220:221]
	v_pk_mul_f32 v[36:37], v[36:37], v[220:221]
	v_pk_mul_f32 v[38:39], v[38:39], v[220:221]
	v_pk_mul_f32 v[40:41], v[40:41], v[220:221]
	v_pk_mul_f32 v[42:43], v[42:43], v[220:221]
	v_pk_mul_f32 v[44:45], v[44:45], v[220:221]
	v_pk_mul_f32 v[46:47], v[46:47], v[220:221]
	v_add_f32_e32 v203, v222, v223
	v_fma_f32 v201, v201, v220, v203
	v_cvt_pk_bf16_f32 v48, v0, v1
	v_cvt_pk_bf16_f32 v49, v2, v3
	v_cvt_pk_bf16_f32 v50, v4, v5
	v_cvt_pk_bf16_f32 v51, v6, v7
	v_cvt_pk_bf16_f32 v52, v8, v9
	v_cvt_pk_bf16_f32 v53, v10, v11
	v_cvt_pk_bf16_f32 v54, v12, v13
	v_cvt_pk_bf16_f32 v55, v14, v15
	v_cvt_pk_bf16_f32 v56, v16, v17
	v_cvt_pk_bf16_f32 v57, v18, v19
	v_cvt_pk_bf16_f32 v58, v20, v21
	v_cvt_pk_bf16_f32 v59, v22, v23
	v_cvt_pk_bf16_f32 v60, v24, v25
	v_cvt_pk_bf16_f32 v61, v26, v27
	v_cvt_pk_bf16_f32 v62, v28, v29
	v_cvt_pk_bf16_f32 v63, v30, v31
	s_waitcnt lgkmcnt(7)
	v_mfma_f32_16x16x32_bf16 v[32:35], v[112:115], v[48:51], v[32:35]
	ds_read_b128 v[112:115], v227 offset:32768
	s_waitcnt lgkmcnt(7)
	v_mfma_f32_16x16x32_bf16 v[36:39], v[116:119], v[48:51], v[36:39]
	ds_read_b128 v[116:119], v227 offset:36864
	s_waitcnt lgkmcnt(7)
	v_mfma_f32_16x16x32_bf16 v[40:43], v[120:123], v[48:51], v[40:43]
	ds_read_b128 v[120:123], v227 offset:40960
	s_waitcnt lgkmcnt(7)
	v_mfma_f32_16x16x32_bf16 v[44:47], v[124:127], v[48:51], v[44:47]
	ds_read_b128 v[124:127], v227 offset:45056
	s_waitcnt lgkmcnt(7)
	v_mfma_f32_16x16x32_bf16 v[32:35], v[128:131], v[52:55], v[32:35]
	ds_read_b128 v[128:131], v228 offset:32768
	s_waitcnt lgkmcnt(7)
	v_mfma_f32_16x16x32_bf16 v[36:39], v[132:135], v[52:55], v[36:39]
	ds_read_b128 v[132:135], v228 offset:36864
	s_waitcnt lgkmcnt(7)
	v_mfma_f32_16x16x32_bf16 v[40:43], v[136:139], v[52:55], v[40:43]
	ds_read_b128 v[136:139], v228 offset:40960
	s_waitcnt lgkmcnt(7)
	v_mfma_f32_16x16x32_bf16 v[44:47], v[140:143], v[52:55], v[44:47]
	ds_read_b128 v[140:143], v228 offset:45056
	s_waitcnt lgkmcnt(7)
	v_mfma_f32_16x16x32_bf16 v[32:35], v[112:115], v[56:59], v[32:35]
	s_waitcnt lgkmcnt(6)
	v_mfma_f32_16x16x32_bf16 v[36:39], v[116:119], v[56:59], v[36:39]
	s_waitcnt lgkmcnt(5)
	v_mfma_f32_16x16x32_bf16 v[40:43], v[120:123], v[56:59], v[40:43]
	s_waitcnt lgkmcnt(4)
	v_mfma_f32_16x16x32_bf16 v[44:47], v[124:127], v[56:59], v[44:47]
	s_waitcnt lgkmcnt(3)
	v_mfma_f32_16x16x32_bf16 v[32:35], v[128:131], v[60:63], v[32:35]
	s_waitcnt lgkmcnt(2)
	v_mfma_f32_16x16x32_bf16 v[36:39], v[132:135], v[60:63], v[36:39]
	s_waitcnt lgkmcnt(1)
	v_mfma_f32_16x16x32_bf16 v[40:43], v[136:139], v[60:63], v[40:43]
	s_waitcnt lgkmcnt(0)
	v_mfma_f32_16x16x32_bf16 v[44:47], v[140:143], v[60:63], v[44:47]
	ds_read_b32 v0, v184 offset:384
	ds_read_b32 v1, v185 offset:384
	ds_read_b32 v2, v186 offset:384
	ds_read_b32 v3, v187 offset:384
	ds_read_b32 v4, v184 offset:512
	ds_read_b32 v5, v185 offset:512
	ds_read_b32 v6, v186 offset:512
	ds_read_b32 v7, v187 offset:512
	ds_read_b32 v8, v188 offset:384
	ds_read_b32 v9, v189 offset:384
	ds_read_b32 v10, v190 offset:384
	ds_read_b32 v11, v191 offset:384
	ds_read_b32 v12, v188 offset:512
	ds_read_b32 v13, v189 offset:512
	ds_read_b32 v14, v190 offset:512
	ds_read_b32 v15, v191 offset:512
	s_waitcnt lgkmcnt(0)
	v_mov_b32_e32 v205, v201
	s_nop 1
	v_permlane16_swap_b32_e32 v201, v205
	v_add_f32_e32 v201, v201, v205
	v_mov_b32_e32 v205, v201
	s_nop 1
	v_permlane32_swap_b32_e32 v201, v205
	v_add_f32_e32 v201, v201, v205
	v_rcp_f32_e32 v203, v201
	s_nop 7
	v_mul_f32_e32 v32, v32, v203
	v_mul_f32_e32 v33, v33, v203
	v_mul_f32_e32 v34, v34, v203
	v_mul_f32_e32 v35, v35, v203
	v_mul_f32_e32 v36, v36, v203
	v_mul_f32_e32 v37, v37, v203
	v_mul_f32_e32 v38, v38, v203
	v_mul_f32_e32 v39, v39, v203
	v_mul_f32_e32 v40, v40, v203
	v_mul_f32_e32 v41, v41, v203
	v_mul_f32_e32 v42, v42, v203
	v_mul_f32_e32 v43, v43, v203
	v_mul_f32_e32 v44, v44, v203
	v_mul_f32_e32 v45, v45, v203
	v_mul_f32_e32 v46, v46, v203
	v_mul_f32_e32 v47, v47, v203
	v_cvt_pk_bf16_f32 v210, v32, v33
	v_cvt_pk_bf16_f32 v211, v34, v35
	v_cvt_pk_bf16_f32 v212, v36, v37
	v_cvt_pk_bf16_f32 v213, v38, v39
	v_cvt_pk_bf16_f32 v214, v40, v41
	v_cvt_pk_bf16_f32 v215, v42, v43
	v_cvt_pk_bf16_f32 v216, v44, v45
	v_cvt_pk_bf16_f32 v217, v46, v47
	global_store_dwordx2 v167, v[210:211], s[98:99] offset:0
	global_store_dwordx2 v167, v[212:213], s[98:99] offset:32
	global_store_dwordx2 v167, v[214:215], s[98:99] offset:64
	global_store_dwordx2 v167, v[216:217], s[98:99] offset:96
	v_mov_b32_e32 v200, 0xf149f2ca
	v_mov_b32_e32 v201, 0
	v_mov_b32_e32 v32, 0
	v_mov_b32_e32 v33, 0
	v_mov_b32_e32 v34, 0
	v_mov_b32_e32 v35, 0
	v_mov_b32_e32 v36, 0
	v_mov_b32_e32 v37, 0
	v_mov_b32_e32 v38, 0
	v_mov_b32_e32 v39, 0
	v_mov_b32_e32 v40, 0
	v_mov_b32_e32 v41, 0
	v_mov_b32_e32 v42, 0
	v_mov_b32_e32 v43, 0
	v_mov_b32_e32 v44, 0
	v_mov_b32_e32 v45, 0
	v_mov_b32_e32 v46, 0
	v_mov_b32_e32 v47, 0
	v_mov_b32_e32 v64, v72
	v_mov_b32_e32 v65, v73
	v_mov_b32_e32 v66, v74
	v_mov_b32_e32 v67, v75
	v_mov_b32_e32 v68, v76
	v_mov_b32_e32 v69, v77
	v_mov_b32_e32 v70, v78
	v_mov_b32_e32 v71, v79
	s_add_u32 s3, s3, 1
	s_and_b32 s0, s3, 0xff
	s_cmp_lt_u32 s0, 16
	s_cbranch_scc1 .Lmy_att_tile
	s_waitcnt vmcnt(0)
	s_branch .LBB0_1501
